# DeltaNet solve: the 32 serial right-hand-side row loads (one shared register, vmcnt(0) each) now load into their final registers and stay in flight together
# speedup vs baseline: 1.0195x; 1.0195x over previous
; #define LAS __attribute__((address_space(3)))
; __device__ __forceinline__ void solve_diag(float (&x)[64], const LAS float* AT, const int o, const int ja, const int jb) {
; #pragma unroll
;     for (int j = ja; j < jb; ++j) { const float xj = x[o + j];
;         int z = 0; if (j >= 2) asm("" : "+v"(z) : "v"(x[o + j - 2]));
;         const LAS float* ATj = AT + z;
; #pragma unroll
;         for (int i4 = ((j + 1) >> 2) << 2; i4 < 32; i4 += 4) { const f32x4 av = *(const LAS f32x4*)(ATj + j * 36 + i4);
; #pragma unroll
;             for (int t = 0; t < 4; ++t) if (i4 + t > j) x[o + i4 + t] -= av[t] * xj; } }
; __device__ __forceinline__ void phase_gdn_solve(const Args& a, LAS unsigned char* lds, const WCtx& w, int l) {
;     ...
;         if (live) {
; #pragma unroll
;             for (int i = 0; i < 32; i += 4) { const f32x4 sc = *(const LAS f32x4*)(BETA + 64 * wv + i);
; #pragma unroll
;                 for (int t = 0; t < 4; ++t) x[i + t] *= sc[t]; }
;             solve_diag(x, A11T, 0, 0, 16);
.LBB0_1062:
	s_and_b64 vcc, exec, s[0:1]
	s_waitcnt lgkmcnt(0)
	s_barrier
	s_cbranch_vccnz .LBB0_1043
	v_mov_b32_e32 v214, s39
	ds_read_b128 v[14:17], v214 offset:32512
	ds_read_b128 v[8:11], v214 offset:32528
	ds_read_b128 v[24:27], v214 offset:32544
	ds_read_b128 v[28:31], v214 offset:32560
	v_mov_b32_e32 v191, v137
	s_waitcnt lgkmcnt(3)
	v_pk_mul_f32 v[162:163], v[156:157], v[14:15] op_sel:[0,1] op_sel_hi:[1,0]
	v_mov_b32_e32 v157, s27
	ds_read_b128 v[4:7], v214 offset:32576
	ds_read_b128 v[18:21], v214 offset:32592
	ds_read_b128 v[38:41], v214 offset:32608
	ds_read_b128 v[12:15], v214 offset:32624
	ds_read_b128 v[54:57], v157 offset:9216
	ds_read_b128 v[72:75], v157 offset:9232
	ds_read_b128 v[46:49], v157 offset:9248
	ds_read_b128 v[32:35], v157 offset:9264
	s_waitcnt lgkmcnt(8)
	v_mov_b32_e32 v192, v31
	v_mov_b32_e32 v193, v28
	v_mov_b32_e32 v2, v29
	v_mov_b32_e32 v3, v30
	ds_read_b128 v[108:111], v157 offset:9280
	ds_read_b128 v[28:31], v157 offset:9296
	ds_read_b128 v[66:69], v157 offset:9312
	s_waitcnt lgkmcnt(3)
	v_mov_b32_e32 v22, v33
	v_mov_b32_e32 v23, v34
	v_mov_b32_e32 v137, v139
	v_pk_mul_f32 v[22:23], v[162:163], v[22:23] op_sel:[1,0]
	v_fma_f32 v156, -v163, v55, v162
	v_pk_fma_f32 v[188:189], v[136:137], v[2:3], v[22:23] neg_lo:[0,0,1] neg_hi:[0,0,1]
	v_mov_b32_e32 v2, v35
	v_mov_b32_e32 v3, v32
	v_pk_mul_f32 v[200:201], v[162:163], v[2:3] op_sel:[1,0]
	s_waitcnt lgkmcnt(0)
	v_pk_mul_f32 v[2:3], v[162:163], v[66:67] op_sel:[1,0]
	v_mov_b32_e32 v190, v138
	v_pk_fma_f32 v[206:207], v[64:65], v[38:39], v[2:3] op_sel:[1,0,0] op_sel_hi:[0,1,1] neg_lo:[0,0,1] neg_hi:[0,0,1]
	v_mov_b32_e32 v2, v51
	ds_read_b128 v[36:39], v157 offset:9328
	ds_read_b128 v[88:91], v157 offset:9376
	ds_read_b128 v[76:79], v157 offset:9392
	ds_read_b128 v[52:55], v157 offset:9408
	v_lshl_add_u32 v22, v2, 2, s27
	v_pk_mul_f32 v[2:3], v[162:163], v[56:57] op_sel:[1,0]
	ds_read_b128 v[116:119], v157 offset:9424
	ds_read_b128 v[32:35], v157 offset:9440
	ds_read_b128 v[80:83], v157 offset:9456
	ds_read_b128 v[112:115], v157 offset:9472
	ds_read_b128 v[64:67], v22 offset:9504
	ds_read_b128 v[98:101], v22 offset:9520
	ds_read_b128 v[84:87], v22 offset:9536
	ds_read_b128 v[42:45], v22 offset:9552
	v_pk_fma_f32 v[2:3], v[152:153], v[16:17], v[2:3] op_sel:[1,0,0] op_sel_hi:[0,1,1] neg_lo:[0,0,1] neg_hi:[0,0,1]
	ds_read_b64 v[16:17], v157 offset:9368
	ds_read_b128 v[128:131], v22 offset:9568
	ds_read_b128 v[56:59], v22 offset:9584
	ds_read_b128 v[92:95], v22 offset:9600
	ds_read_b128 v[136:139], v22 offset:9616
	v_mov_b32_e32 v97, v123
	v_mov_b32_e32 v123, v124
	s_waitcnt lgkmcnt(4)
	v_pk_fma_f32 v[164:165], v[156:157], v[16:17], v[2:3] op_sel_hi:[0,1,1] neg_lo:[1,0,0] neg_hi:[1,0,0]
	v_pk_mul_f32 v[2:3], v[162:163], v[68:69] op_sel:[1,0]
	v_fma_f32 v152, -v164, v67, v165
	v_pk_fma_f32 v[2:3], v[62:63], v[40:41], v[2:3] op_sel:[1,0,0] op_sel_hi:[0,1,1] neg_lo:[0,0,1] neg_hi:[0,0,1]
	v_pk_fma_f32 v[2:3], v[156:157], v[82:83], v[2:3] op_sel_hi:[0,1,1] neg_lo:[1,0,0] neg_hi:[1,0,0]
	s_waitcnt lgkmcnt(1)
	v_pk_fma_f32 v[194:195], v[164:165], v[94:95], v[2:3] op_sel_hi:[0,1,1] neg_lo:[1,0,0] neg_hi:[1,0,0]
	v_mov_b32_e32 v2, v51
	v_mov_b32_e32 v17, v72
	v_lshl_add_u32 v16, v2, 2, s27
	ds_read_b128 v[132:135], v16 offset:9664
	ds_read_b128 v[102:105], v16 offset:9680
	ds_read_b128 v[68:71], v16 offset:9696
	ds_read_b128 v[166:169], v16 offset:9712
	v_pk_mul_f32 v[2:3], v[162:163], v[108:109] op_sel:[1,0]
	v_pk_mul_f32 v[40:41], v[162:163], v[110:111] op_sel:[1,0]
	v_pk_fma_f32 v[2:3], v[60:61], v[4:5], v[2:3] op_sel:[1,0,0] op_sel_hi:[0,1,1] neg_lo:[0,0,1] neg_hi:[0,0,1]
	v_pk_fma_f32 v[2:3], v[156:157], v[116:117], v[2:3] op_sel_hi:[0,1,1] neg_lo:[1,0,0] neg_hi:[1,0,0]
	v_pk_fma_f32 v[2:3], v[164:165], v[128:129], v[2:3] op_sel_hi:[0,1,1] neg_lo:[1,0,0] neg_hi:[1,0,0]
	s_waitcnt lgkmcnt(0)
	v_pk_fma_f32 v[174:175], v[152:153], v[166:167], v[2:3] op_sel_hi:[0,1,1] neg_lo:[1,0,0] neg_hi:[1,0,0]
	v_mov_b32_e32 v2, v51
	ds_read_b128 v[60:63], v16 offset:9728
	ds_read_b128 v[64:67], v16 offset:9744
	ds_read_b128 v[170:173], v16 offset:9760
	v_mov_b32_e32 v16, v75
	v_lshl_add_u32 v22, v2, 2, s27
	v_mov_b32_e32 v2, v158
	v_mov_b32_e32 v3, v155
	v_mov_b32_e32 v4, v11
	v_mov_b32_e32 v5, v8
	v_pk_mul_f32 v[16:17], v[162:163], v[16:17] op_sel:[1,0]
	v_mov_b32_e32 v155, v159
	v_pk_fma_f32 v[2:3], v[2:3], v[4:5], v[16:17] neg_lo:[0,0,1] neg_hi:[0,0,1]
	v_mov_b32_e32 v4, v91
	v_mov_b32_e32 v5, v88
	v_pk_fma_f32 v[2:3], v[156:157], v[4:5], v[2:3] op_sel_hi:[0,1,1] neg_lo:[1,0,0] neg_hi:[1,0,0]
	v_mov_b32_e32 v4, v101
	v_mov_b32_e32 v5, v98
	v_pk_fma_f32 v[2:3], v[164:165], v[4:5], v[2:3] op_sel_hi:[0,1,1] neg_lo:[1,0,0] neg_hi:[1,0,0]
	v_mov_b32_e32 v4, v135
	v_mov_b32_e32 v5, v132
	v_pk_fma_f32 v[166:167], v[152:153], v[4:5], v[2:3] op_sel_hi:[0,1,1] neg_lo:[1,0,0] neg_hi:[1,0,0]
	v_mov_b32_e32 v4, v73
	v_mov_b32_e32 v5, v74
	v_mov_b32_e32 v2, v9
	v_mov_b32_e32 v3, v10
	v_pk_mul_f32 v[4:5], v[162:163], v[4:5] op_sel:[1,0]
	v_pk_fma_f32 v[6:7], v[120:121], v[6:7], v[40:41] op_sel:[1,0,0] op_sel_hi:[0,1,1] neg_lo:[0,0,1] neg_hi:[0,0,1]
	v_pk_fma_f32 v[2:3], v[154:155], v[2:3], v[4:5] neg_lo:[0,0,1] neg_hi:[0,0,1]
	v_mov_b32_e32 v4, v89
	v_mov_b32_e32 v5, v90
	v_pk_fma_f32 v[2:3], v[156:157], v[4:5], v[2:3] op_sel_hi:[0,1,1] neg_lo:[1,0,0] neg_hi:[1,0,0]
	v_mov_b32_e32 v4, v99
	v_mov_b32_e32 v5, v100
	v_pk_fma_f32 v[2:3], v[164:165], v[4:5], v[2:3] op_sel_hi:[0,1,1] neg_lo:[1,0,0] neg_hi:[1,0,0]
	v_mov_b32_e32 v4, v133
	v_mov_b32_e32 v5, v134
	v_pk_fma_f32 v[16:17], v[152:153], v[4:5], v[2:3] op_sel_hi:[0,1,1] neg_lo:[1,0,0] neg_hi:[1,0,0]
	ds_read_b128 v[8:11], v22 offset:9808
	ds_read_b128 v[106:109], v22 offset:9824
	ds_read_b128 v[88:91], v22 offset:9840
	ds_read_b128 v[2:5], v22 offset:9856
	ds_read_b128 v[140:143], v22 offset:9872
	ds_read_b128 v[72:75], v22 offset:9888
	ds_read_b128 v[178:181], v22 offset:9904
	s_waitcnt lgkmcnt(6)
; #define LAS __attribute__((address_space(3)))
; __device__ __forceinline__ void solve_diag(float (&x)[64], const LAS float* AT, const int o, const int ja, const int jb) {
; #pragma unroll
;     for (int j = ja; j < jb; ++j) { const float xj = x[o + j];
;         int z = 0; if (j >= 2) asm("" : "+v"(z) : "v"(x[o + j - 2]));
;         const LAS float* ATj = AT + z;
; #pragma unroll
;         for (int i4 = ((j + 1) >> 2) << 2; i4 < 32; i4 += 4) { const f32x4 av = *(const LAS f32x4*)(ATj + j * 36 + i4);
; #pragma unroll
;             for (int t = 0; t < 4; ++t) if (i4 + t > j) x[o + i4 + t] -= av[t] * xj; } }
	v_mov_b32_e32 v8, v9
	v_mov_b32_e32 v9, v10
	v_pk_fma_f32 v[154:155], v[166:167], v[8:9], v[16:17] op_sel:[1,0,0] neg_lo:[1,0,0] neg_hi:[1,0,0]
	v_fma_f32 v17, -v167, v11, v166
	v_mov_b32_e32 v10, v39
	v_mov_b32_e32 v11, v36
	v_mov_b32_e32 v8, v15
	v_mov_b32_e32 v9, v12
	v_pk_mul_f32 v[10:11], v[162:163], v[10:11] op_sel:[1,0]
	v_pk_fma_f32 v[6:7], v[156:157], v[118:119], v[6:7] op_sel_hi:[0,1,1] neg_lo:[1,0,0] neg_hi:[1,0,0]
	v_pk_fma_f32 v[8:9], v[96:97], v[8:9], v[10:11] neg_lo:[0,0,1] neg_hi:[0,0,1]
	v_mov_b32_e32 v10, v115
	v_mov_b32_e32 v11, v112
	v_pk_fma_f32 v[8:9], v[156:157], v[10:11], v[8:9] op_sel_hi:[0,1,1] neg_lo:[1,0,0] neg_hi:[1,0,0]
	v_mov_b32_e32 v10, v139
	v_mov_b32_e32 v11, v136
	v_pk_fma_f32 v[8:9], v[164:165], v[10:11], v[8:9] op_sel_hi:[0,1,1] neg_lo:[1,0,0] neg_hi:[1,0,0]
	v_mov_b32_e32 v10, v173
	v_mov_b32_e32 v11, v170
	v_pk_fma_f32 v[8:9], v[152:153], v[10:11], v[8:9] op_sel_hi:[0,1,1] neg_lo:[1,0,0] neg_hi:[1,0,0]
	s_waitcnt lgkmcnt(0)
	v_mov_b32_e32 v10, v181
	v_mov_b32_e32 v11, v178
	v_pk_fma_f32 v[204:205], v[166:167], v[10:11], v[8:9] op_sel:[1,0,0] neg_lo:[1,0,0] neg_hi:[1,0,0]
	v_mov_b32_e32 v8, v51
	v_pk_fma_f32 v[6:7], v[164:165], v[130:131], v[6:7] op_sel_hi:[0,1,1] neg_lo:[1,0,0] neg_hi:[1,0,0]
	v_lshl_add_u32 v12, v8, 2, s27
	ds_read_b64 v[22:23], v12 offset:9960
	ds_read_b128 v[132:135], v12 offset:9968
	ds_read_b128 v[98:101], v12 offset:9984
	ds_read_b128 v[8:11], v12 offset:10000
	ds_read_b128 v[144:147], v12 offset:10016
	v_pk_fma_f32 v[6:7], v[152:153], v[168:169], v[6:7] op_sel_hi:[0,1,1] neg_lo:[1,0,0] neg_hi:[1,0,0]
	v_pk_fma_f32 v[4:5], v[166:167], v[4:5], v[6:7] op_sel:[1,0,0] neg_lo:[1,0,0] neg_hi:[1,0,0]
	v_mov_b32_e32 v16, v155
	s_waitcnt lgkmcnt(1)
	v_pk_fma_f32 v[176:177], v[154:155], v[10:11], v[4:5] op_sel_hi:[0,1,1] neg_lo:[1,0,0] neg_hi:[1,0,0]
	ds_read_b128 v[94:97], v12 offset:10032
	ds_read_b128 v[4:7], v12 offset:10048
	v_mov_b32_e32 v10, v13
	v_mov_b32_e32 v12, v37
	v_mov_b32_e32 v13, v38
	v_mov_b32_e32 v11, v14
	v_pk_mul_f32 v[12:13], v[162:163], v[12:13] op_sel:[1,0]
	s_waitcnt lgkmcnt(0)
	v_mov_b32_e32 v209, v4
	v_pk_fma_f32 v[10:11], v[122:123], v[10:11], v[12:13] neg_lo:[0,0,1] neg_hi:[0,0,1]
	v_mov_b32_e32 v12, v113
	v_mov_b32_e32 v13, v114
	v_pk_fma_f32 v[10:11], v[156:157], v[12:13], v[10:11] op_sel_hi:[0,1,1] neg_lo:[1,0,0] neg_hi:[1,0,0]
	v_mov_b32_e32 v12, v137
	v_mov_b32_e32 v13, v138
	v_pk_fma_f32 v[10:11], v[164:165], v[12:13], v[10:11] op_sel_hi:[0,1,1] neg_lo:[1,0,0] neg_hi:[1,0,0]
	v_mov_b32_e32 v12, v171
	v_mov_b32_e32 v13, v172
	v_pk_fma_f32 v[10:11], v[152:153], v[12:13], v[10:11] op_sel_hi:[0,1,1] neg_lo:[1,0,0] neg_hi:[1,0,0]
	v_mov_b32_e32 v12, v179
	v_mov_b32_e32 v13, v180
	v_mov_b32_e32 v4, v51
	v_pk_fma_f32 v[10:11], v[166:167], v[12:13], v[10:11] op_sel:[1,0,0] neg_lo:[1,0,0] neg_hi:[1,0,0]
	v_mov_b32_e32 v12, v5
	v_mov_b32_e32 v13, v6
	v_pk_fma_f32 v[180:181], v[154:155], v[12:13], v[10:11] op_sel_hi:[0,1,1] neg_lo:[1,0,0] neg_hi:[1,0,0]
	v_lshl_add_u32 v14, v4, 2, s27
	v_mov_b32_e32 v208, v7
	ds_read_b128 v[10:13], v14 offset:10096
	ds_read_b128 v[170:173], v14 offset:10112
	ds_read_b128 v[110:113], v14 offset:10128
	ds_read_b128 v[4:7], v14 offset:10144
	v_pk_fma_f32 v[168:169], v[154:155], v[22:23], v[16:17] op_sel_hi:[0,1,1] neg_lo:[1,0,0] neg_hi:[1,0,0]
	v_mov_b32_e32 v22, v31
	v_mov_b32_e32 v23, v28
	ds_read_b128 v[182:185], v14 offset:10160
	ds_read_b128 v[114:117], v14 offset:10176
	ds_read_b128 v[128:131], v14 offset:10192
	s_waitcnt lgkmcnt(6)
	v_mov_b32_e32 v10, v51
	v_mov_b32_e32 v14, v160
	v_mov_b32_e32 v15, v127
	v_mov_b32_e32 v16, v21
	v_mov_b32_e32 v17, v18
	v_pk_mul_f32 v[22:23], v[162:163], v[22:23] op_sel:[1,0]
	v_fma_f32 v158, -v168, v13, v169
	v_lshl_add_u32 v36, v10, 2, s27
	v_pk_fma_f32 v[14:15], v[14:15], v[16:17], v[22:23] neg_lo:[0,0,1] neg_hi:[0,0,1]
	v_mov_b32_e32 v16, v35
	v_mov_b32_e32 v17, v32
	ds_read_b128 v[216:219], v36 offset:10256
	ds_read_b128 v[122:125], v36 offset:10272
	ds_read_b128 v[10:13], v36 offset:10288
	ds_read_b128 v[220:223], v36 offset:10304
	v_pk_fma_f32 v[14:15], v[156:157], v[16:17], v[14:15] op_sel_hi:[0,1,1] neg_lo:[1,0,0] neg_hi:[1,0,0]
	v_mov_b32_e32 v16, v59
	v_mov_b32_e32 v17, v56
	v_pk_fma_f32 v[14:15], v[164:165], v[16:17], v[14:15] op_sel_hi:[0,1,1] neg_lo:[1,0,0] neg_hi:[1,0,0]
	v_mov_b32_e32 v16, v63
	v_mov_b32_e32 v17, v60
	v_pk_fma_f32 v[14:15], v[152:153], v[16:17], v[14:15] op_sel_hi:[0,1,1] neg_lo:[1,0,0] neg_hi:[1,0,0]
	v_mov_b32_e32 v16, v143
	v_mov_b32_e32 v17, v140
	v_pk_fma_f32 v[14:15], v[166:167], v[16:17], v[14:15] op_sel:[1,0,0] neg_lo:[1,0,0] neg_hi:[1,0,0]
	v_mov_b32_e32 v16, v147
	v_mov_b32_e32 v17, v144
	v_pk_fma_f32 v[14:15], v[154:155], v[16:17], v[14:15] op_sel_hi:[0,1,1] neg_lo:[1,0,0] neg_hi:[1,0,0]
	s_waitcnt lgkmcnt(6)
	v_mov_b32_e32 v16, v185
	v_mov_b32_e32 v17, v182
	v_mov_b32_e32 v18, v19
	v_mov_b32_e32 v19, v20
	v_mov_b32_e32 v20, v29
	v_mov_b32_e32 v21, v30
	v_pk_fma_f32 v[14:15], v[168:169], v[16:17], v[14:15] op_sel_hi:[0,1,1] neg_lo:[1,0,0] neg_hi:[1,0,0]
	s_waitcnt lgkmcnt(0)
; #define LAS __attribute__((address_space(3)))
; __device__ __forceinline__ void solve_diag(float (&x)[64], const LAS float* AT, const int o, const int ja, const int jb) {
; #pragma unroll
;     for (int j = ja; j < jb; ++j) { const float xj = x[o + j];
;         int z = 0; if (j >= 2) asm("" : "+v"(z) : "v"(x[o + j - 2]));
;         const LAS float* ATj = AT + z;
; #pragma unroll
;         for (int i4 = ((j + 1) >> 2) << 2; i4 < 32; i4 += 4) { const f32x4 av = *(const LAS f32x4*)(ATj + j * 36 + i4);
; #pragma unroll
;             for (int t = 0; t < 4; ++t) if (i4 + t > j) x[o + i4 + t] -= av[t] * xj; } }
	v_mov_b32_e32 v16, v223
	v_mov_b32_e32 v17, v220
	v_pk_mul_f32 v[22:23], v[162:163], v[46:47] op_sel:[1,0]
	v_mov_b32_e32 v127, v161
	v_pk_mul_f32 v[20:21], v[162:163], v[20:21] op_sel:[1,0]
	v_pk_fma_f32 v[178:179], v[158:159], v[16:17], v[14:15] op_sel_hi:[0,1,1] neg_lo:[1,0,0] neg_hi:[1,0,0]
	v_mov_b32_e32 v14, v51
	v_pk_fma_f32 v[22:23], v[148:149], v[24:25], v[22:23] op_sel:[1,0,0] op_sel_hi:[0,1,1] neg_lo:[0,0,1] neg_hi:[0,0,1]
	v_pk_fma_f32 v[18:19], v[126:127], v[18:19], v[20:21] neg_lo:[0,0,1] neg_hi:[0,0,1]
	v_mov_b32_e32 v20, v33
	v_mov_b32_e32 v21, v34
	v_pk_fma_f32 v[22:23], v[156:157], v[76:77], v[22:23] op_sel_hi:[0,1,1] neg_lo:[1,0,0] neg_hi:[1,0,0]
	v_lshl_add_u32 v28, v14, 2, s27
	v_pk_fma_f32 v[18:19], v[156:157], v[20:21], v[18:19] op_sel_hi:[0,1,1] neg_lo:[1,0,0] neg_hi:[1,0,0]
	v_mov_b32_e32 v20, v57
	v_mov_b32_e32 v21, v58
	ds_read_b128 v[118:121], v36 offset:10320
	ds_read_b128 v[38:41], v36 offset:10336
	ds_read_b128 v[242:245], v28 offset:10400
	ds_read_b128 v[136:139], v28 offset:10416
	ds_read_b128 v[14:17], v28 offset:10432
	ds_read_b128 v[246:249], v28 offset:10448
	v_pk_fma_f32 v[22:23], v[164:165], v[84:85], v[22:23] op_sel_hi:[0,1,1] neg_lo:[1,0,0] neg_hi:[1,0,0]
	v_pk_fma_f32 v[18:19], v[164:165], v[20:21], v[18:19] op_sel_hi:[0,1,1] neg_lo:[1,0,0] neg_hi:[1,0,0]
	v_mov_b32_e32 v20, v61
	v_mov_b32_e32 v21, v62
	v_pk_fma_f32 v[22:23], v[152:153], v[102:103], v[22:23] op_sel_hi:[0,1,1] neg_lo:[1,0,0] neg_hi:[1,0,0]
	v_pk_fma_f32 v[18:19], v[152:153], v[20:21], v[18:19] op_sel_hi:[0,1,1] neg_lo:[1,0,0] neg_hi:[1,0,0]
	v_mov_b32_e32 v20, v141
	v_mov_b32_e32 v21, v142
	v_pk_fma_f32 v[22:23], v[166:167], v[106:107], v[22:23] op_sel:[1,0,0] neg_lo:[1,0,0] neg_hi:[1,0,0]
	v_pk_fma_f32 v[18:19], v[166:167], v[20:21], v[18:19] op_sel:[1,0,0] neg_lo:[1,0,0] neg_hi:[1,0,0]
	v_mov_b32_e32 v20, v145
	v_mov_b32_e32 v21, v146
	v_pk_fma_f32 v[22:23], v[154:155], v[132:133], v[22:23] op_sel_hi:[0,1,1] neg_lo:[1,0,0] neg_hi:[1,0,0]
	v_pk_fma_f32 v[18:19], v[154:155], v[20:21], v[18:19] op_sel_hi:[0,1,1] neg_lo:[1,0,0] neg_hi:[1,0,0]
	v_mov_b32_e32 v20, v183
	v_mov_b32_e32 v21, v184
	v_pk_fma_f32 v[22:23], v[168:169], v[170:171], v[22:23] op_sel_hi:[0,1,1] neg_lo:[1,0,0] neg_hi:[1,0,0]
	v_pk_fma_f32 v[18:19], v[168:169], v[20:21], v[18:19] op_sel_hi:[0,1,1] neg_lo:[1,0,0] neg_hi:[1,0,0]
	v_mov_b32_e32 v20, v221
	v_mov_b32_e32 v21, v222
	v_pk_fma_f32 v[170:171], v[158:159], v[216:217], v[22:23] op_sel_hi:[0,1,1] neg_lo:[1,0,0] neg_hi:[1,0,0]
	v_pk_fma_f32 v[18:19], v[158:159], v[20:21], v[18:19] op_sel_hi:[0,1,1] neg_lo:[1,0,0] neg_hi:[1,0,0]
	s_waitcnt lgkmcnt(0)
	v_mov_b32_e32 v20, v247
	v_mov_b32_e32 v21, v248
	v_pk_fma_f32 v[160:161], v[170:171], v[20:21], v[18:19] op_sel_hi:[0,1,1] neg_lo:[1,0,0] neg_hi:[1,0,0]
	v_mov_b32_e32 v18, v51
	v_pk_mul_f32 v[46:47], v[162:163], v[48:49] op_sel:[1,0]
	v_lshl_add_u32 v18, v18, 2, s27
	v_pk_fma_f32 v[26:27], v[150:151], v[26:27], v[46:47] op_sel:[1,0,0] op_sel_hi:[0,1,1] neg_lo:[0,0,1] neg_hi:[0,0,1]
	ds_read_b128 v[140:143], v28 offset:10464
	ds_read_b128 v[56:59], v28 offset:10480
	ds_read_b64 v[28:29], v18 offset:10552
	ds_read_b128 v[220:223], v18 offset:10560
	ds_read_b128 v[30:33], v18 offset:10576
	ds_read_b128 v[22:25], v18 offset:10592
	ds_read_b128 v[144:147], v18 offset:10608
	v_pk_fma_f32 v[26:27], v[156:157], v[78:79], v[26:27] op_sel_hi:[0,1,1] neg_lo:[1,0,0] neg_hi:[1,0,0]
	v_pk_fma_f32 v[26:27], v[164:165], v[86:87], v[26:27] op_sel_hi:[0,1,1] neg_lo:[1,0,0] neg_hi:[1,0,0]
	v_pk_fma_f32 v[26:27], v[152:153], v[104:105], v[26:27] op_sel_hi:[0,1,1] neg_lo:[1,0,0] neg_hi:[1,0,0]
	ds_read_b128 v[60:63], v18 offset:10624
	v_mov_b32_e32 v18, v51
	v_pk_fma_f32 v[26:27], v[166:167], v[108:109], v[26:27] op_sel:[1,0,0] neg_lo:[1,0,0] neg_hi:[1,0,0]
	v_pk_fma_f32 v[80:81], v[156:157], v[80:81], v[206:207] op_sel_hi:[0,1,1] neg_lo:[1,0,0] neg_hi:[1,0,0]
	s_waitcnt lgkmcnt(2)
	v_mov_b32_e32 v182, v23
	v_pk_fma_f32 v[26:27], v[154:155], v[134:135], v[26:27] op_sel_hi:[0,1,1] neg_lo:[1,0,0] neg_hi:[1,0,0]
	v_lshl_add_u32 v23, v18, 2, s27
	v_pk_fma_f32 v[80:81], v[164:165], v[92:93], v[80:81] op_sel_hi:[0,1,1] neg_lo:[1,0,0] neg_hi:[1,0,0]
	v_mov_b32_e32 v184, v249
	v_mov_b32_e32 v185, v246
	ds_read_b128 v[82:85], v23 offset:10688
	ds_read_b128 v[246:249], v23 offset:10704
	ds_read_b128 v[34:37], v23 offset:10720
	ds_read_b128 v[18:21], v23 offset:10736
	v_pk_fma_f32 v[26:27], v[168:169], v[172:173], v[26:27] op_sel_hi:[0,1,1] neg_lo:[1,0,0] neg_hi:[1,0,0]
	ds_read_b128 v[102:105], v23 offset:10752
	ds_read_b128 v[76:79], v23 offset:10768
	v_mov_b32_e32 v23, v51
	v_pk_fma_f32 v[64:65], v[152:153], v[64:65], v[80:81] op_sel_hi:[0,1,1] neg_lo:[1,0,0] neg_hi:[1,0,0]
	v_fma_f32 v148, -v170, v243, v171
	v_pk_fma_f32 v[26:27], v[158:159], v[218:219], v[26:27] op_sel_hi:[0,1,1] neg_lo:[1,0,0] neg_hi:[1,0,0]
	v_pk_fma_f32 v[64:65], v[166:167], v[72:73], v[64:65] op_sel:[1,0,0] neg_lo:[1,0,0] neg_hi:[1,0,0]
	v_pk_fma_f32 v[26:27], v[170:171], v[244:245], v[26:27] op_sel_hi:[0,1,1] neg_lo:[1,0,0] neg_hi:[1,0,0]
	v_lshl_add_u32 v23, v23, 2, s27
	v_pk_fma_f32 v[64:65], v[154:155], v[94:95], v[64:65] op_sel_hi:[0,1,1] neg_lo:[1,0,0] neg_hi:[1,0,0]
	v_pk_fma_f32 v[172:173], v[148:149], v[28:29], v[26:27] op_sel_hi:[0,1,1] neg_lo:[1,0,0] neg_hi:[1,0,0]
	ds_read_b128 v[106:109], v23 offset:10848
	ds_read_b128 v[46:49], v23 offset:10864
	ds_read_b128 v[26:29], v23 offset:10880
	ds_read_b128 v[132:135], v23 offset:10896
	v_pk_fma_f32 v[64:65], v[168:169], v[114:115], v[64:65] op_sel_hi:[0,1,1] neg_lo:[1,0,0] neg_hi:[1,0,0]
	v_pk_fma_f32 v[64:65], v[158:159], v[118:119], v[64:65] op_sel_hi:[0,1,1] neg_lo:[1,0,0] neg_hi:[1,0,0]
	v_pk_fma_f32 v[64:65], v[170:171], v[140:141], v[64:65] op_sel_hi:[0,1,1] neg_lo:[1,0,0] neg_hi:[1,0,0]
	s_waitcnt lgkmcnt(11)
; #define LAS __attribute__((address_space(3)))
; __device__ __forceinline__ void solve_diag(float (&x)[64], const LAS float* AT, const int o, const int ja, const int jb) {
; #pragma unroll
;     for (int j = ja; j < jb; ++j) { const float xj = x[o + j];
;         int z = 0; if (j >= 2) asm("" : "+v"(z) : "v"(x[o + j - 2]));
;         const LAS float* ATj = AT + z;
; #pragma unroll
;         for (int i4 = ((j + 1) >> 2) << 2; i4 < 32; i4 += 4) { const f32x4 av = *(const LAS f32x4*)(ATj + j * 36 + i4);
; #pragma unroll
;             for (int t = 0; t < 4; ++t) if (i4 + t > j) x[o + i4 + t] -= av[t] * xj; } }
	v_pk_fma_f32 v[64:65], v[148:149], v[144:145], v[64:65] op_sel_hi:[0,1,1] neg_lo:[1,0,0] neg_hi:[1,0,0]
	s_waitcnt lgkmcnt(9)
	v_fma_f32 v150, -v172, v85, v173
	s_waitcnt lgkmcnt(5)
	v_pk_fma_f32 v[64:65], v[172:173], v[102:103], v[64:65] op_sel_hi:[0,1,1] neg_lo:[1,0,0] neg_hi:[1,0,0]
	v_mov_b32_e32 v203, v54
	s_waitcnt lgkmcnt(0)
	v_pk_fma_f32 v[144:145], v[150:151], v[132:133], v[64:65] op_sel_hi:[0,1,1] neg_lo:[1,0,0] neg_hi:[1,0,0]
	v_pk_fma_f32 v[64:65], v[190:191], v[192:193], v[200:201] neg_lo:[0,0,1] neg_hi:[0,0,1]
	v_mov_b32_e32 v54, v55
	v_mov_b32_e32 v55, v52
	v_mov_b32_e32 v202, v53
	v_pk_fma_f32 v[52:53], v[156:157], v[54:55], v[64:65] op_sel_hi:[0,1,1] neg_lo:[1,0,0] neg_hi:[1,0,0]
	v_mov_b32_e32 v54, v45
	v_mov_b32_e32 v55, v42
	v_pk_fma_f32 v[52:53], v[164:165], v[54:55], v[52:53] op_sel_hi:[0,1,1] neg_lo:[1,0,0] neg_hi:[1,0,0]
	v_mov_b32_e32 v54, v71
	v_mov_b32_e32 v55, v68
	v_pk_fma_f32 v[52:53], v[152:153], v[54:55], v[52:53] op_sel_hi:[0,1,1] neg_lo:[1,0,0] neg_hi:[1,0,0]
	v_mov_b32_e32 v54, v91
	v_mov_b32_e32 v55, v88
	v_pk_fma_f32 v[52:53], v[166:167], v[54:55], v[52:53] op_sel:[1,0,0] neg_lo:[1,0,0] neg_hi:[1,0,0]
	v_mov_b32_e32 v54, v101
	v_mov_b32_e32 v55, v98
	v_pk_fma_f32 v[52:53], v[154:155], v[54:55], v[52:53] op_sel_hi:[0,1,1] neg_lo:[1,0,0] neg_hi:[1,0,0]
	v_mov_b32_e32 v54, v113
	v_mov_b32_e32 v55, v110
	v_pk_fma_f32 v[52:53], v[168:169], v[54:55], v[52:53] op_sel_hi:[0,1,1] neg_lo:[1,0,0] neg_hi:[1,0,0]
	v_mov_b32_e32 v54, v125
	v_mov_b32_e32 v55, v122
	v_pk_fma_f32 v[52:53], v[158:159], v[54:55], v[52:53] op_sel_hi:[0,1,1] neg_lo:[1,0,0] neg_hi:[1,0,0]
	v_mov_b32_e32 v54, v139
	v_mov_b32_e32 v55, v136
	v_pk_fma_f32 v[52:53], v[170:171], v[54:55], v[52:53] op_sel_hi:[0,1,1] neg_lo:[1,0,0] neg_hi:[1,0,0]
	v_mov_b32_e32 v54, v223
	v_mov_b32_e32 v55, v220
	v_pk_fma_f32 v[52:53], v[148:149], v[54:55], v[52:53] op_sel_hi:[0,1,1] neg_lo:[1,0,0] neg_hi:[1,0,0]
	v_mov_b32_e32 v54, v249
	v_mov_b32_e32 v55, v246
	v_pk_fma_f32 v[52:53], v[172:173], v[54:55], v[52:53] op_sel_hi:[0,1,1] neg_lo:[1,0,0] neg_hi:[1,0,0]
	v_mov_b32_e32 v54, v109
	v_mov_b32_e32 v55, v106
	v_pk_fma_f32 v[140:141], v[150:151], v[54:55], v[52:53] op_sel_hi:[0,1,1] neg_lo:[1,0,0] neg_hi:[1,0,0]
	v_pk_fma_f32 v[52:53], v[156:157], v[202:203], v[188:189] op_sel_hi:[0,1,1] neg_lo:[1,0,0] neg_hi:[1,0,0]
	v_mov_b32_e32 v42, v43
	v_mov_b32_e32 v43, v44
	v_pk_fma_f32 v[42:43], v[164:165], v[42:43], v[52:53] op_sel_hi:[0,1,1] neg_lo:[1,0,0] neg_hi:[1,0,0]
	v_mov_b32_e32 v44, v69
	v_mov_b32_e32 v45, v70
	v_pk_fma_f32 v[42:43], v[152:153], v[44:45], v[42:43] op_sel_hi:[0,1,1] neg_lo:[1,0,0] neg_hi:[1,0,0]
	v_mov_b32_e32 v44, v89
	v_mov_b32_e32 v45, v90
	v_pk_fma_f32 v[42:43], v[166:167], v[44:45], v[42:43] op_sel:[1,0,0] neg_lo:[1,0,0] neg_hi:[1,0,0]
	v_mov_b32_e32 v44, v99
	v_mov_b32_e32 v45, v100
	v_pk_fma_f32 v[42:43], v[154:155], v[44:45], v[42:43] op_sel_hi:[0,1,1] neg_lo:[1,0,0] neg_hi:[1,0,0]
	v_mov_b32_e32 v44, v111
	v_mov_b32_e32 v45, v112
	v_pk_fma_f32 v[42:43], v[168:169], v[44:45], v[42:43] op_sel_hi:[0,1,1] neg_lo:[1,0,0] neg_hi:[1,0,0]
	v_mov_b32_e32 v44, v123
	v_mov_b32_e32 v45, v124
	v_pk_fma_f32 v[42:43], v[158:159], v[44:45], v[42:43] op_sel_hi:[0,1,1] neg_lo:[1,0,0] neg_hi:[1,0,0]
	v_mov_b32_e32 v44, v137
	v_mov_b32_e32 v45, v138
	ds_read_b128 v[84:87], v23 offset:10912
	v_mov_b32_e32 v23, v51
	v_pk_fma_f32 v[42:43], v[170:171], v[44:45], v[42:43] op_sel_hi:[0,1,1] neg_lo:[1,0,0] neg_hi:[1,0,0]
	v_mov_b32_e32 v44, v221
	v_mov_b32_e32 v45, v222
	v_pk_fma_f32 v[42:43], v[148:149], v[44:45], v[42:43] op_sel_hi:[0,1,1] neg_lo:[1,0,0] neg_hi:[1,0,0]
	v_mov_b32_e32 v44, v247
	v_mov_b32_e32 v45, v248
	v_lshl_add_u32 v23, v23, 2, s27
	v_pk_fma_f32 v[42:43], v[172:173], v[44:45], v[42:43] op_sel_hi:[0,1,1] neg_lo:[1,0,0] neg_hi:[1,0,0]
	v_mov_b32_e32 v44, v107
	v_mov_b32_e32 v45, v108
	v_pk_fma_f32 v[64:65], v[150:151], v[44:45], v[42:43] op_sel_hi:[0,1,1] neg_lo:[1,0,0] neg_hi:[1,0,0]
	ds_read_b128 v[52:55], v23 offset:10992
	ds_read_b128 v[92:95], v23 offset:11008
	ds_read_b128 v[68:71], v23 offset:11024
	ds_read_b128 v[42:45], v23 offset:11040
	ds_read_b128 v[108:111], v23 offset:11056
	s_waitcnt lgkmcnt(4)
	v_mov_b32_e32 v52, v53
	v_mov_b32_e32 v53, v54
	v_pk_fma_f32 v[136:137], v[140:141], v[52:53], v[64:65] op_sel:[1,0,0] neg_lo:[1,0,0] neg_hi:[1,0,0]
	v_pk_fma_f32 v[64:65], v[152:153], v[66:67], v[194:195] op_sel_hi:[0,1,1] neg_lo:[1,0,0] neg_hi:[1,0,0]
	v_pk_fma_f32 v[64:65], v[166:167], v[74:75], v[64:65] op_sel:[1,0,0] neg_lo:[1,0,0] neg_hi:[1,0,0]
	v_mov_b32_e32 v23, v51
	v_pk_fma_f32 v[64:65], v[154:155], v[96:97], v[64:65] op_sel_hi:[0,1,1] neg_lo:[1,0,0] neg_hi:[1,0,0]
	v_pk_fma_f32 v[64:65], v[168:169], v[116:117], v[64:65] op_sel_hi:[0,1,1] neg_lo:[1,0,0] neg_hi:[1,0,0]
	v_pk_fma_f32 v[64:65], v[158:159], v[120:121], v[64:65] op_sel_hi:[0,1,1] neg_lo:[1,0,0] neg_hi:[1,0,0]
	v_lshl_add_u32 v23, v23, 2, s27
	v_pk_fma_f32 v[64:65], v[170:171], v[142:143], v[64:65] op_sel_hi:[0,1,1] neg_lo:[1,0,0] neg_hi:[1,0,0]
	v_fma_f32 v99, -v141, v55, v140
	ds_read_b64 v[118:119], v23 offset:11144
	ds_read_b128 v[100:103], v23 offset:11152
	ds_read_b128 v[80:83], v23 offset:11168
	ds_read_b128 v[52:55], v23 offset:11184
	ds_read_b128 v[112:115], v23 offset:11200
	v_pk_fma_f32 v[64:65], v[148:149], v[146:147], v[64:65] op_sel_hi:[0,1,1] neg_lo:[1,0,0] neg_hi:[1,0,0]
	v_pk_fma_f32 v[64:65], v[172:173], v[104:105], v[64:65] op_sel_hi:[0,1,1] neg_lo:[1,0,0] neg_hi:[1,0,0]
	v_pk_fma_f32 v[64:65], v[150:151], v[134:135], v[64:65] op_sel_hi:[0,1,1] neg_lo:[1,0,0] neg_hi:[1,0,0]
	v_mov_b32_e32 v23, v51
	s_waitcnt lgkmcnt(6)
; #define LAS __attribute__((address_space(3)))
; __device__ __forceinline__ float bf2f(unsigned b) { return __uint_as_float(b << 16); }
; __device__ __forceinline__ void solve_diag(float (&x)[64], const LAS float* AT, const int o, const int ja, const int jb) {
; #pragma unroll
;     for (int j = ja; j < jb; ++j) { const float xj = x[o + j];
;         int z = 0; if (j >= 2) asm("" : "+v"(z) : "v"(x[o + j - 2]));
;         const LAS float* ATj = AT + z;
; #pragma unroll
;         for (int i4 = ((j + 1) >> 2) << 2; i4 < 32; i4 += 4) { const f32x4 av = *(const LAS f32x4*)(ATj + j * 36 + i4);
; #pragma unroll
;             for (int t = 0; t < 4; ++t) if (i4 + t > j) x[o + i4 + t] -= av[t] * xj; } }
; __device__ __forceinline__ void phase_gdn_solve(const Args& a, LAS unsigned char* lds, const WCtx& w, int l) {
;     ...
;             { long zz = 0; asm volatile("" : "+v"(zz) : "v"(x[15]));
;               const bf16* xp = PB + (size_t)row0 * NPB + (wv == 0 ? 512 : 256) + h * 64 + lane + zz;
; #pragma unroll
;               for (int i = 32; i < 64; ++i) x[i] = bf2f(xp[sg * i * NPB]); }
;             solve_diag(x, A11T, 0, 16, 31);
	v_pk_fma_f32 v[44:45], v[140:141], v[44:45], v[64:65] op_sel:[1,0,0] neg_lo:[1,0,0] neg_hi:[1,0,0]
	v_mov_b32_e32 v187, v130
	s_waitcnt lgkmcnt(1)
	v_pk_fma_f32 v[54:55], v[136:137], v[54:55], v[44:45] op_sel_hi:[0,1,1] neg_lo:[1,0,0] neg_hi:[1,0,0]
	v_lshl_add_u32 v23, v23, 2, s27
	v_pk_fma_f32 v[44:45], v[154:155], v[208:209], v[204:205] op_sel_hi:[0,1,1] neg_lo:[1,0,0] neg_hi:[1,0,0]
	v_mov_b32_e32 v130, v131
	v_mov_b32_e32 v131, v128
	v_mov_b32_e32 v186, v129
	ds_read_b128 v[72:75], v23 offset:11280
	ds_read_b128 v[104:107], v23 offset:11296
	ds_read_b128 v[88:91], v23 offset:11312
	ds_read_b128 v[64:67], v23 offset:11328
	ds_read_b128 v[120:123], v23 offset:11344
	v_mov_b32_e32 v23, v51
	v_pk_fma_f32 v[44:45], v[168:169], v[130:131], v[44:45] op_sel_hi:[0,1,1] neg_lo:[1,0,0] neg_hi:[1,0,0]
	v_mov_b32_e32 v128, v41
	v_mov_b32_e32 v129, v38
	v_mov_b32_e32 v98, v137
	v_pk_fma_f32 v[44:45], v[158:159], v[128:129], v[44:45] op_sel_hi:[0,1,1] neg_lo:[1,0,0] neg_hi:[1,0,0]
	v_mov_b32_e32 v128, v59
	v_mov_b32_e32 v129, v56
	v_pk_fma_f32 v[142:143], v[136:137], v[118:119], v[98:99] op_sel_hi:[0,1,1] neg_lo:[1,0,0] neg_hi:[1,0,0]
	v_lshl_add_u32 v23, v23, 2, s27
	v_pk_fma_f32 v[44:45], v[170:171], v[128:129], v[44:45] op_sel_hi:[0,1,1] neg_lo:[1,0,0] neg_hi:[1,0,0]
	v_mov_b32_e32 v128, v63
	v_mov_b32_e32 v129, v60
	s_waitcnt lgkmcnt(4)
	v_fma_f32 v138, -v142, v75, v143
	ds_read_b128 v[116:119], v23 offset:11440
	ds_read_b128 v[96:99], v23 offset:11456
	ds_read_b128 v[72:75], v23 offset:11472
	ds_read_b128 v[124:127], v23 offset:11488
	v_pk_fma_f32 v[44:45], v[148:149], v[128:129], v[44:45] op_sel_hi:[0,1,1] neg_lo:[1,0,0] neg_hi:[1,0,0]
	v_mov_b32_e32 v128, v79
	v_mov_b32_e32 v129, v76
	v_pk_fma_f32 v[44:45], v[172:173], v[128:129], v[44:45] op_sel_hi:[0,1,1] neg_lo:[1,0,0] neg_hi:[1,0,0]
	v_mov_b32_e32 v128, v87
	v_mov_b32_e32 v129, v84
	v_pk_fma_f32 v[44:45], v[150:151], v[128:129], v[44:45] op_sel_hi:[0,1,1] neg_lo:[1,0,0] neg_hi:[1,0,0]
	v_mov_b32_e32 v128, v111
	v_mov_b32_e32 v129, v108
	v_pk_fma_f32 v[44:45], v[140:141], v[128:129], v[44:45] op_sel:[1,0,0] neg_lo:[1,0,0] neg_hi:[1,0,0]
	v_mov_b32_e32 v128, v115
	v_mov_b32_e32 v129, v112
	s_add_u32 s0, s30, s71
	v_pk_fma_f32 v[44:45], v[136:137], v[128:129], v[44:45] op_sel_hi:[0,1,1] neg_lo:[1,0,0] neg_hi:[1,0,0]
	s_waitcnt lgkmcnt(4)
	v_mov_b32_e32 v128, v123
	v_mov_b32_e32 v129, v120
	s_addc_u32 s1, s31, s11
	s_lshl_b32 s2, s70, 7
	v_pk_fma_f32 v[44:45], v[142:143], v[128:129], v[44:45] op_sel_hi:[0,1,1] neg_lo:[1,0,0] neg_hi:[1,0,0]
	s_waitcnt lgkmcnt(0)
	v_mov_b32_e32 v128, v127
	v_mov_b32_e32 v129, v124
	s_add_u32 s0, s0, s2
	v_pk_fma_f32 v[146:147], v[138:139], v[128:129], v[44:45] op_sel_hi:[0,1,1] neg_lo:[1,0,0] neg_hi:[1,0,0]
	v_mov_b64_e32 v[44:45], 0
	s_addc_u32 s1, s1, 0
	v_lshl_add_u64 v[128:129], s[0:1], 0, v[50:51]
	v_lshl_add_u64 v[44:45], v[44:45], 1, v[128:129]
	v_mov_b32_e32 v23, 0x14000
	v_mad_u64_u32 v[44:45], s[0:1], s12, v23, v[44:45]
	s_mul_i32 s13, s13, 0x14000
	v_add_u32_e32 v45, s13, v45
	global_load_ushort v63, v[44:45], off
	v_mad_u64_u32 v[44:45], s[0:1], s12, v233, v[44:45]
	v_add_u32_e32 v45, s10, v45
	v_pk_fma_f32 v[2:3], v[166:167], v[2:3], v[174:175] op_sel:[1,0,0] neg_lo:[1,0,0] neg_hi:[1,0,0]
	v_pk_fma_f32 v[6:7], v[168:169], v[6:7], v[176:177] op_sel_hi:[0,1,1] neg_lo:[1,0,0] neg_hi:[1,0,0]
	v_pk_fma_f32 v[2:3], v[154:155], v[8:9], v[2:3] op_sel_hi:[0,1,1] neg_lo:[1,0,0] neg_hi:[1,0,0]
	v_pk_fma_f32 v[2:3], v[168:169], v[4:5], v[2:3] op_sel_hi:[0,1,1] neg_lo:[1,0,0] neg_hi:[1,0,0]
	v_mov_b32_e32 v4, v39
	v_mov_b32_e32 v5, v40
	v_mov_b32_e32 v183, v24
	s_mul_i32 s68, s68, 36
	s_and_b64 vcc, exec, s[4:5]
	global_load_ushort v84, v[44:45], off
	v_mad_u64_u32 v[44:45], s[0:1], s12, v233, v[44:45]
	v_add_u32_e32 v45, s10, v45
	global_load_ushort v87, v[44:45], off
	v_mad_u64_u32 v[44:45], s[0:1], s12, v233, v[44:45]
	v_add_u32_e32 v45, s10, v45
	global_load_ushort v108, v[44:45], off
	v_mad_u64_u32 v[44:45], s[0:1], s12, v233, v[44:45]
	v_add_u32_e32 v45, s10, v45
	global_load_ushort v111, v[44:45], off
	v_mad_u64_u32 v[44:45], s[0:1], s12, v233, v[44:45]
	v_add_u32_e32 v45, s10, v45
	global_load_ushort v112, v[44:45], off
	v_mad_u64_u32 v[44:45], s[0:1], s12, v233, v[44:45]
	v_add_u32_e32 v45, s10, v45
	global_load_ushort v115, v[44:45], off
	v_mad_u64_u32 v[44:45], s[0:1], s12, v233, v[44:45]
	v_add_u32_e32 v45, s10, v45
	global_load_ushort v139, v[44:45], off
	v_mad_u64_u32 v[44:45], s[0:1], s12, v233, v[44:45]
	v_add_u32_e32 v45, s10, v45
	global_load_ushort v149, v[44:45], off
	v_mad_u64_u32 v[44:45], s[0:1], s12, v233, v[44:45]
	v_add_u32_e32 v45, s10, v45
	global_load_ushort v151, v[44:45], off
	v_mad_u64_u32 v[44:45], s[0:1], s12, v233, v[44:45]
	v_add_u32_e32 v45, s10, v45
	global_load_ushort v153, v[44:45], off
	v_mad_u64_u32 v[44:45], s[0:1], s12, v233, v[44:45]
	v_add_u32_e32 v45, s10, v45
	global_load_ushort v159, v[44:45], off
	v_mad_u64_u32 v[44:45], s[0:1], s12, v233, v[44:45]
	v_add_u32_e32 v45, s10, v45
	global_load_ushort v162, v[44:45], off
	v_mad_u64_u32 v[44:45], s[0:1], s12, v233, v[44:45]
	v_add_u32_e32 v45, s10, v45
	v_pk_fma_f32 v[2:3], v[158:159], v[10:11], v[2:3] op_sel_hi:[0,1,1] neg_lo:[1,0,0] neg_hi:[1,0,0]
	v_pk_fma_f32 v[2:3], v[170:171], v[14:15], v[2:3] op_sel_hi:[0,1,1] neg_lo:[1,0,0] neg_hi:[1,0,0]
	v_pk_fma_f32 v[2:3], v[148:149], v[30:31], v[2:3] op_sel_hi:[0,1,1] neg_lo:[1,0,0] neg_hi:[1,0,0]
	v_pk_fma_f32 v[2:3], v[172:173], v[34:35], v[2:3] op_sel_hi:[0,1,1] neg_lo:[1,0,0] neg_hi:[1,0,0]
	v_pk_fma_f32 v[2:3], v[150:151], v[46:47], v[2:3] op_sel_hi:[0,1,1] neg_lo:[1,0,0] neg_hi:[1,0,0]
; #define LAS __attribute__((address_space(3)))
; __device__ __forceinline__ float bf2f(unsigned b) { return __uint_as_float(b << 16); }
; __device__ __forceinline__ void solve_diag(float (&x)[64], const LAS float* AT, const int o, const int ja, const int jb) {
; #pragma unroll
;     for (int j = ja; j < jb; ++j) { const float xj = x[o + j];
;         int z = 0; if (j >= 2) asm("" : "+v"(z) : "v"(x[o + j - 2]));
;         const LAS float* ATj = AT + z;
; #pragma unroll
;         for (int i4 = ((j + 1) >> 2) << 2; i4 < 32; i4 += 4) { const f32x4 av = *(const LAS f32x4*)(ATj + j * 36 + i4);
; #pragma unroll
;             for (int t = 0; t < 4; ++t) if (i4 + t > j) x[o + i4 + t] -= av[t] * xj; } }
; __device__ __forceinline__ void phase_gdn_solve(const Args& a, LAS unsigned char* lds, const WCtx& w, int l) {
;     ...
;             { long zz = 0; asm volatile("" : "+v"(zz) : "v"(x[15]));
;               const bf16* xp = PB + (size_t)row0 * NPB + (wv == 0 ? 512 : 256) + h * 64 + lane + zz;
; #pragma unroll
;               for (int i = 32; i < 64; ++i) x[i] = bf2f(xp[sg * i * NPB]); }
;             solve_diag(x, A11T, 0, 16, 31);
	v_pk_fma_f32 v[2:3], v[140:141], v[92:93], v[2:3] op_sel:[1,0,0] neg_lo:[1,0,0] neg_hi:[1,0,0]
	v_pk_fma_f32 v[6:7], v[158:159], v[12:13], v[6:7] op_sel_hi:[0,1,1] neg_lo:[1,0,0] neg_hi:[1,0,0]
	v_pk_fma_f32 v[2:3], v[136:137], v[100:101], v[2:3] op_sel_hi:[0,1,1] neg_lo:[1,0,0] neg_hi:[1,0,0]
	v_pk_fma_f32 v[2:3], v[142:143], v[104:105], v[2:3] op_sel_hi:[0,1,1] neg_lo:[1,0,0] neg_hi:[1,0,0]
	v_pk_fma_f32 v[92:93], v[138:139], v[116:117], v[2:3] op_sel_hi:[0,1,1] neg_lo:[1,0,0] neg_hi:[1,0,0]
	v_pk_fma_f32 v[2:3], v[168:169], v[186:187], v[180:181] op_sel_hi:[0,1,1] neg_lo:[1,0,0] neg_hi:[1,0,0]
	v_pk_fma_f32 v[2:3], v[158:159], v[4:5], v[2:3] op_sel_hi:[0,1,1] neg_lo:[1,0,0] neg_hi:[1,0,0]
	v_mov_b32_e32 v4, v57
	v_mov_b32_e32 v5, v58
	v_pk_fma_f32 v[2:3], v[170:171], v[4:5], v[2:3] op_sel_hi:[0,1,1] neg_lo:[1,0,0] neg_hi:[1,0,0]
	v_mov_b32_e32 v4, v61
	v_mov_b32_e32 v5, v62
	v_pk_fma_f32 v[2:3], v[148:149], v[4:5], v[2:3] op_sel_hi:[0,1,1] neg_lo:[1,0,0] neg_hi:[1,0,0]
	v_mov_b32_e32 v4, v77
	v_mov_b32_e32 v5, v78
	v_pk_fma_f32 v[2:3], v[172:173], v[4:5], v[2:3] op_sel_hi:[0,1,1] neg_lo:[1,0,0] neg_hi:[1,0,0]
	v_mov_b32_e32 v4, v85
	v_mov_b32_e32 v5, v86
	v_pk_fma_f32 v[2:3], v[150:151], v[4:5], v[2:3] op_sel_hi:[0,1,1] neg_lo:[1,0,0] neg_hi:[1,0,0]
	v_mov_b32_e32 v4, v109
	v_mov_b32_e32 v5, v110
	v_pk_fma_f32 v[2:3], v[140:141], v[4:5], v[2:3] op_sel:[1,0,0] neg_lo:[1,0,0] neg_hi:[1,0,0]
	v_mov_b32_e32 v4, v113
	v_mov_b32_e32 v5, v114
	v_pk_fma_f32 v[2:3], v[136:137], v[4:5], v[2:3] op_sel_hi:[0,1,1] neg_lo:[1,0,0] neg_hi:[1,0,0]
	v_mov_b32_e32 v4, v121
	v_mov_b32_e32 v5, v122
	v_pk_fma_f32 v[2:3], v[142:143], v[4:5], v[2:3] op_sel_hi:[0,1,1] neg_lo:[1,0,0] neg_hi:[1,0,0]
	v_mov_b32_e32 v4, v125
	v_mov_b32_e32 v5, v126
	v_pk_fma_f32 v[6:7], v[170:171], v[16:17], v[6:7] op_sel_hi:[0,1,1] neg_lo:[1,0,0] neg_hi:[1,0,0]
	v_pk_fma_f32 v[2:3], v[138:139], v[4:5], v[2:3] op_sel_hi:[0,1,1] neg_lo:[1,0,0] neg_hi:[1,0,0]
	v_pk_fma_f32 v[6:7], v[148:149], v[32:33], v[6:7] op_sel_hi:[0,1,1] neg_lo:[1,0,0] neg_hi:[1,0,0]
	v_pk_fma_f32 v[6:7], v[172:173], v[36:37], v[6:7] op_sel_hi:[0,1,1] neg_lo:[1,0,0] neg_hi:[1,0,0]
	v_pk_fma_f32 v[6:7], v[150:151], v[48:49], v[6:7] op_sel_hi:[0,1,1] neg_lo:[1,0,0] neg_hi:[1,0,0]
	v_pk_fma_f32 v[6:7], v[140:141], v[94:95], v[6:7] op_sel:[1,0,0] neg_lo:[1,0,0] neg_hi:[1,0,0]
	v_mov_b32_e32 v16, v25
	v_pk_fma_f32 v[6:7], v[136:137], v[102:103], v[6:7] op_sel_hi:[0,1,1] neg_lo:[1,0,0] neg_hi:[1,0,0]
	v_pk_fma_f32 v[6:7], v[142:143], v[106:107], v[6:7] op_sel_hi:[0,1,1] neg_lo:[1,0,0] neg_hi:[1,0,0]
	v_pk_fma_f32 v[6:7], v[138:139], v[118:119], v[6:7] op_sel_hi:[0,1,1] neg_lo:[1,0,0] neg_hi:[1,0,0]
	v_mov_b32_e32 v17, v22
	global_load_ushort v165, v[44:45], off
	v_mad_u64_u32 v[44:45], s[0:1], s12, v233, v[44:45]
	v_add_u32_e32 v45, s10, v45
	global_load_ushort v188, v[44:45], off
	v_mad_u64_u32 v[44:45], s[0:1], s12, v233, v[44:45]
	v_add_u32_e32 v45, s10, v45
	global_load_ushort v189, v[44:45], off
	v_mad_u64_u32 v[44:45], s[0:1], s12, v233, v[44:45]
	v_add_u32_e32 v45, s10, v45
	global_load_ushort v190, v[44:45], off
	v_mad_u64_u32 v[44:45], s[0:1], s12, v233, v[44:45]
	v_add_u32_e32 v45, s10, v45
	global_load_ushort v191, v[44:45], off
	v_mad_u64_u32 v[44:45], s[0:1], s12, v233, v[44:45]
	v_add_u32_e32 v45, s10, v45
	global_load_ushort v192, v[44:45], off
	v_mad_u64_u32 v[44:45], s[0:1], s12, v233, v[44:45]
	v_add_u32_e32 v45, s10, v45
	global_load_ushort v193, v[44:45], off
	v_mad_u64_u32 v[44:45], s[0:1], s12, v233, v[44:45]
	v_add_u32_e32 v45, s10, v45
	global_load_ushort v194, v[44:45], off
	v_mad_u64_u32 v[44:45], s[0:1], s12, v233, v[44:45]
	v_add_u32_e32 v45, s10, v45
	global_load_ushort v195, v[44:45], off
	v_mad_u64_u32 v[44:45], s[0:1], s12, v233, v[44:45]
	v_add_u32_e32 v45, s10, v45
	global_load_ushort v200, v[44:45], off
	v_mad_u64_u32 v[44:45], s[0:1], s12, v233, v[44:45]
	v_add_u32_e32 v45, s10, v45
	global_load_ushort v201, v[44:45], off
	v_mad_u64_u32 v[44:45], s[0:1], s12, v233, v[44:45]
	v_add_u32_e32 v45, s10, v45
	global_load_ushort v202, v[44:45], off
	v_mad_u64_u32 v[44:45], s[0:1], s12, v233, v[44:45]
	v_add_u32_e32 v45, s10, v45
	global_load_ushort v203, v[44:45], off
	v_mad_u64_u32 v[44:45], s[0:1], s12, v233, v[44:45]
	v_add_u32_e32 v45, s10, v45
	global_load_ushort v204, v[44:45], off
	v_mad_u64_u32 v[44:45], s[0:1], s12, v233, v[44:45]
	v_add_u32_e32 v45, s10, v45
	global_load_ushort v205, v[44:45], off
	v_mad_u64_u32 v[44:45], s[0:1], s12, v233, v[44:45]
	v_add_u32_e32 v45, s10, v45
	global_load_ushort v206, v[44:45], off
	v_mad_u64_u32 v[44:45], s[0:1], s12, v233, v[44:45]
	v_add_u32_e32 v45, s10, v45
	global_load_ushort v207, v[44:45], off
	v_mad_u64_u32 v[44:45], s[0:1], s12, v233, v[44:45]
	v_add_u32_e32 v45, s10, v45
	global_load_ushort v208, v[44:45], off
	v_mad_u64_u32 v[44:45], s[0:1], s12, v233, v[44:45]
	v_add_u32_e32 v45, s10, v45
	s_movk_i32 s0, 0x90
	global_load_ushort v209, v[44:45], off
	s_waitcnt vmcnt(0)
; #define LAS __attribute__((address_space(3)))
; __device__ __forceinline__ float bf2f(unsigned b) { return __uint_as_float(b << 16); }
; __device__ __forceinline__ void solve_diag(float (&x)[64], const LAS float* AT, const int o, const int ja, const int jb) {
; #pragma unroll
;     for (int j = ja; j < jb; ++j) { const float xj = x[o + j];
;         int z = 0; if (j >= 2) asm("" : "+v"(z) : "v"(x[o + j - 2]));
;         const LAS float* ATj = AT + z;
; #pragma unroll
;         for (int i4 = ((j + 1) >> 2) << 2; i4 < 32; i4 += 4) { const f32x4 av = *(const LAS f32x4*)(ATj + j * 36 + i4);
; #pragma unroll
;             for (int t = 0; t < 4; ++t) if (i4 + t > j) x[o + i4 + t] -= av[t] * xj; } }
; __device__ __forceinline__ void phase_gdn_solve(const Args& a, LAS unsigned char* lds, const WCtx& w, int l) {
;     ...
;               for (int i = 32; i < 64; ++i) x[i] = bf2f(xp[sg * i * NPB]); }
	v_lshlrev_b32_e32 v63, 16, v63
	v_lshlrev_b32_e32 v84, 16, v84
	v_lshlrev_b32_e32 v87, 16, v87
	v_lshlrev_b32_e32 v108, 16, v108
	v_lshlrev_b32_e32 v111, 16, v111
	v_lshlrev_b32_e32 v112, 16, v112
	v_lshlrev_b32_e32 v115, 16, v115
	v_lshlrev_b32_e32 v139, 16, v139
	v_lshlrev_b32_e32 v149, 16, v149
	v_lshlrev_b32_e32 v151, 16, v151
	v_lshlrev_b32_e32 v153, 16, v153
	v_lshlrev_b32_e32 v159, 16, v159
	v_lshlrev_b32_e32 v162, 16, v162
	v_lshlrev_b32_e32 v165, 16, v165
	v_lshlrev_b32_e32 v188, 16, v188
	v_lshlrev_b32_e32 v189, 16, v189
	v_lshlrev_b32_e32 v190, 16, v190
	v_lshlrev_b32_e32 v191, 16, v191
	v_lshlrev_b32_e32 v192, 16, v192
	v_lshlrev_b32_e32 v193, 16, v193
	v_lshlrev_b32_e32 v194, 16, v194
	v_lshlrev_b32_e32 v195, 16, v195
	v_lshlrev_b32_e32 v200, 16, v200
	v_lshlrev_b32_e32 v201, 16, v201
	v_lshlrev_b32_e32 v202, 16, v202
	v_lshlrev_b32_e32 v203, 16, v203
	v_lshlrev_b32_e32 v204, 16, v204
	v_lshlrev_b32_e32 v205, 16, v205
	v_lshlrev_b32_e32 v206, 16, v206
	v_lshlrev_b32_e32 v207, 16, v207
	v_lshlrev_b32_e32 v208, 16, v208
	v_lshlrev_b32_e32 v209, 16, v209
	v_mov_b32_e32 v23, v51
	s_nop 0
	v_lshl_add_u32 v23, v23, 2, s27
	ds_read_b128 v[216:219], v23 offset:11584
	ds_read_b128 v[132:135], v23 offset:11600
	ds_read_b128 v[128:131], v23 offset:11616
	ds_read_b128 v[220:223], v23 offset:11632
	s_waitcnt lgkmcnt(3)
	v_fma_f32 v60, -v92, v217, v93
	v_pk_fma_f32 v[6:7], v[92:93], v[218:219], v[6:7] op_sel_hi:[0,1,1] neg_lo:[1,0,0] neg_hi:[1,0,0]
	s_waitcnt lgkmcnt(0)
	v_mov_b32_e32 v4, v221
	v_mov_b32_e32 v5, v222
	v_pk_fma_f32 v[30:31], v[92:93], v[4:5], v[2:3] op_sel_hi:[0,1,1] neg_lo:[1,0,0] neg_hi:[1,0,0]
	v_mov_b32_e32 v2, v51
	v_mov_b32_e32 v56, v223
	v_lshl_add_u32 v2, v2, 2, s27
	ds_read_b64 v[14:15], v2 offset:11736
	ds_read_b128 v[122:125], v2 offset:11744
	ds_read_b128 v[38:41], v2 offset:11760
	ds_read_b128 v[8:11], v2 offset:11776
	v_mov_b32_e32 v2, v51
	v_mov_b32_e32 v57, v220
	v_lshl_add_u32 v2, v2, 2, s27
	ds_read_b128 v[76:79], v2 offset:11872
	ds_read_b128 v[220:223], v2 offset:11888
	ds_read_b128 v[44:47], v2 offset:11904
	ds_read_b128 v[2:5], v2 offset:11920
	s_waitcnt lgkmcnt(3)
	v_pk_fma_f32 v[76:77], v[60:61], v[14:15], v[6:7] op_sel_hi:[0,1,1] neg_lo:[1,0,0] neg_hi:[1,0,0]
	v_mov_b32_e32 v6, v51
	v_mov_b32_e32 v34, v9
	v_lshl_add_u32 v6, v6, 2, s27
	ds_read_b128 v[100:103], v6 offset:12032
	ds_read_b128 v[104:107], v6 offset:12048
	ds_read_b128 v[12:15], v6 offset:12064
	v_mov_b32_e32 v6, v51
	v_fma_f32 v120, -v76, v79, v77
	v_lshl_add_u32 v9, v6, 2, s27
	v_pk_fma_f32 v[6:7], v[170:171], v[184:185], v[178:179] op_sel_hi:[0,1,1] neg_lo:[1,0,0] neg_hi:[1,0,0]
	v_pk_fma_f32 v[6:7], v[148:149], v[16:17], v[6:7] op_sel_hi:[0,1,1] neg_lo:[1,0,0] neg_hi:[1,0,0]
	v_mov_b32_e32 v16, v21
	v_mov_b32_e32 v17, v18
	v_pk_fma_f32 v[6:7], v[172:173], v[16:17], v[6:7] op_sel_hi:[0,1,1] neg_lo:[1,0,0] neg_hi:[1,0,0]
	v_mov_b32_e32 v16, v29
	v_mov_b32_e32 v17, v26
	v_pk_fma_f32 v[6:7], v[150:151], v[16:17], v[6:7] op_sel_hi:[0,1,1] neg_lo:[1,0,0] neg_hi:[1,0,0]
	v_mov_b32_e32 v16, v71
	v_mov_b32_e32 v17, v68
	v_pk_fma_f32 v[6:7], v[140:141], v[16:17], v[6:7] op_sel:[1,0,0] neg_lo:[1,0,0] neg_hi:[1,0,0]
	v_mov_b32_e32 v16, v83
	v_mov_b32_e32 v17, v80
	v_pk_fma_f32 v[6:7], v[136:137], v[16:17], v[6:7] op_sel_hi:[0,1,1] neg_lo:[1,0,0] neg_hi:[1,0,0]
	v_mov_b32_e32 v16, v91
	v_mov_b32_e32 v17, v88
	v_pk_fma_f32 v[6:7], v[142:143], v[16:17], v[6:7] op_sel_hi:[0,1,1] neg_lo:[1,0,0] neg_hi:[1,0,0]
	v_mov_b32_e32 v16, v99
	v_mov_b32_e32 v17, v96
	v_pk_fma_f32 v[6:7], v[138:139], v[16:17], v[6:7] op_sel_hi:[0,1,1] neg_lo:[1,0,0] neg_hi:[1,0,0]
	v_mov_b32_e32 v16, v135
	v_mov_b32_e32 v17, v132
	v_pk_fma_f32 v[6:7], v[92:93], v[16:17], v[6:7] op_sel_hi:[0,1,1] neg_lo:[1,0,0] neg_hi:[1,0,0]
	v_mov_b32_e32 v16, v125
	v_mov_b32_e32 v17, v122
	v_pk_fma_f32 v[6:7], v[60:61], v[16:17], v[6:7] op_sel_hi:[0,1,1] neg_lo:[1,0,0] neg_hi:[1,0,0]
	s_waitcnt lgkmcnt(5)
	v_mov_b32_e32 v16, v223
	v_mov_b32_e32 v17, v220
	v_pk_fma_f32 v[6:7], v[76:77], v[16:17], v[6:7] op_sel_hi:[0,1,1] neg_lo:[1,0,0] neg_hi:[1,0,0]
	s_waitcnt lgkmcnt(2)
	v_mov_b32_e32 v16, v103
	v_mov_b32_e32 v17, v100
	v_pk_fma_f32 v[78:79], v[120:121], v[16:17], v[6:7] op_sel_hi:[0,1,1] neg_lo:[1,0,0] neg_hi:[1,0,0]
	v_pk_fma_f32 v[6:7], v[148:149], v[182:183], v[160:161] op_sel_hi:[0,1,1] neg_lo:[1,0,0] neg_hi:[1,0,0]
	v_mov_b32_e32 v16, v19
	v_mov_b32_e32 v17, v20
	v_pk_fma_f32 v[6:7], v[172:173], v[16:17], v[6:7] op_sel_hi:[0,1,1] neg_lo:[1,0,0] neg_hi:[1,0,0]
	v_mov_b32_e32 v16, v27
	v_mov_b32_e32 v17, v28
	v_pk_fma_f32 v[6:7], v[150:151], v[16:17], v[6:7] op_sel_hi:[0,1,1] neg_lo:[1,0,0] neg_hi:[1,0,0]
	v_mov_b32_e32 v16, v69
	v_mov_b32_e32 v17, v70
	v_pk_fma_f32 v[6:7], v[140:141], v[16:17], v[6:7] op_sel:[1,0,0] neg_lo:[1,0,0] neg_hi:[1,0,0]
	v_mov_b32_e32 v16, v81
	v_mov_b32_e32 v17, v82
	v_pk_fma_f32 v[6:7], v[136:137], v[16:17], v[6:7] op_sel_hi:[0,1,1] neg_lo:[1,0,0] neg_hi:[1,0,0]
	v_mov_b32_e32 v16, v89
	v_mov_b32_e32 v17, v90
	v_pk_fma_f32 v[6:7], v[142:143], v[16:17], v[6:7] op_sel_hi:[0,1,1] neg_lo:[1,0,0] neg_hi:[1,0,0]
	v_mov_b32_e32 v16, v97
	v_mov_b32_e32 v17, v98
	v_pk_fma_f32 v[6:7], v[138:139], v[16:17], v[6:7] op_sel_hi:[0,1,1] neg_lo:[1,0,0] neg_hi:[1,0,0]
	v_mov_b32_e32 v16, v133
	v_mov_b32_e32 v17, v134
	v_pk_fma_f32 v[6:7], v[92:93], v[16:17], v[6:7] op_sel_hi:[0,1,1] neg_lo:[1,0,0] neg_hi:[1,0,0]
	v_mov_b32_e32 v16, v123
	v_mov_b32_e32 v17, v124
	v_pk_fma_f32 v[6:7], v[60:61], v[16:17], v[6:7] op_sel_hi:[0,1,1] neg_lo:[1,0,0] neg_hi:[1,0,0]
	v_mov_b32_e32 v16, v221
	v_mov_b32_e32 v17, v222
	v_pk_fma_f32 v[6:7], v[76:77], v[16:17], v[6:7] op_sel_hi:[0,1,1] neg_lo:[1,0,0] neg_hi:[1,0,0]
	v_mov_b32_e32 v16, v101
	v_mov_b32_e32 v17, v102
	v_pk_fma_f32 v[6:7], v[120:121], v[16:17], v[6:7] op_sel_hi:[0,1,1] neg_lo:[1,0,0] neg_hi:[1,0,0]
	ds_read_b128 v[16:19], v9 offset:12176
	ds_read_b128 v[20:23], v9 offset:12192
	ds_read_b128 v[24:27], v9 offset:12208
	v_mov_b32_e32 v35, v10
	v_mov_b32_e32 v10, v11
	s_waitcnt lgkmcnt(2)
; #define LAS __attribute__((address_space(3)))
; __device__ __forceinline__ void solve_diag(float (&x)[64], const LAS float* AT, const int o, const int ja, const int jb) {
; #pragma unroll
;     for (int j = ja; j < jb; ++j) { const float xj = x[o + j];
;         int z = 0; if (j >= 2) asm("" : "+v"(z) : "v"(x[o + j - 2]));
;         const LAS float* ATj = AT + z;
; #pragma unroll
;         for (int i4 = ((j + 1) >> 2) << 2; i4 < 32; i4 += 4) { const f32x4 av = *(const LAS f32x4*)(ATj + j * 36 + i4);
; #pragma unroll
;             for (int t = 0; t < 4; ++t) if (i4 + t > j) x[o + i4 + t] -= av[t] * xj; } }
	v_mov_b32_e32 v16, v17
	v_mov_b32_e32 v17, v18
	v_pk_fma_f32 v[126:127], v[78:79], v[16:17], v[6:7] op_sel:[1,0,0] neg_lo:[1,0,0] neg_hi:[1,0,0]
	v_mov_b32_e32 v6, v51
	v_fma_f32 v7, -v79, v19, v78
	v_lshl_add_u32 v6, v6, 2, s27
	ds_read_b64 v[28:29], v6 offset:12328
	ds_read_b128 v[16:19], v6 offset:12336
	ds_read_b128 v[80:83], v6 offset:12352
	v_mov_b32_e32 v6, v51
	v_mov_b32_e32 v11, v8
	v_lshl_add_u32 v6, v6, 2, s27
	ds_read_b128 v[68:71], v6 offset:12464
	ds_read_b128 v[88:91], v6 offset:12480
	ds_read_b128 v[94:97], v6 offset:12496
	v_mov_b32_e32 v6, v127
	s_waitcnt lgkmcnt(2)
	v_pk_fma_f32 v[68:69], v[126:127], v[28:29], v[6:7] op_sel_hi:[0,1,1] neg_lo:[1,0,0] neg_hi:[1,0,0]
	v_mov_b32_e32 v6, v51
	v_fma_f32 v160, -v68, v71, v69
	v_lshl_add_u32 v6, v6, 2, s27
	ds_read_b128 v[98:101], v6 offset:12624
	ds_read_b128 v[116:119], v6 offset:12640
	v_mov_b32_e32 v6, v51
	v_mov_b32_e32 v8, v5
	v_lshl_add_u32 v6, v6, 2, s27
	ds_read_b128 v[122:125], v6 offset:12768
	ds_read_b128 v[132:135], v6 offset:12784
	v_pk_fma_f32 v[6:7], v[140:141], v[42:43], v[144:145] op_sel:[1,0,0] neg_lo:[1,0,0] neg_hi:[1,0,0]
	v_mov_b32_e32 v5, v14
	v_pk_fma_f32 v[6:7], v[136:137], v[52:53], v[6:7] op_sel_hi:[0,1,1] neg_lo:[1,0,0] neg_hi:[1,0,0]
	v_pk_fma_f32 v[6:7], v[142:143], v[64:65], v[6:7] op_sel_hi:[0,1,1] neg_lo:[1,0,0] neg_hi:[1,0,0]
	v_pk_fma_f32 v[6:7], v[138:139], v[72:73], v[6:7] op_sel_hi:[0,1,1] neg_lo:[1,0,0] neg_hi:[1,0,0]
	v_pk_fma_f32 v[6:7], v[92:93], v[128:129], v[6:7] op_sel_hi:[0,1,1] neg_lo:[1,0,0] neg_hi:[1,0,0]
	v_pk_fma_f32 v[6:7], v[60:61], v[38:39], v[6:7] op_sel_hi:[0,1,1] neg_lo:[1,0,0] neg_hi:[1,0,0]
	v_pk_fma_f32 v[6:7], v[76:77], v[44:45], v[6:7] op_sel_hi:[0,1,1] neg_lo:[1,0,0] neg_hi:[1,0,0]
	v_pk_fma_f32 v[6:7], v[120:121], v[104:105], v[6:7] op_sel_hi:[0,1,1] neg_lo:[1,0,0] neg_hi:[1,0,0]
	v_pk_fma_f32 v[6:7], v[78:79], v[20:21], v[6:7] op_sel:[1,0,0] neg_lo:[1,0,0] neg_hi:[1,0,0]
	s_nop 0
	v_pk_fma_f32 v[6:7], v[126:127], v[16:17], v[6:7] op_sel_hi:[0,1,1] neg_lo:[1,0,0] neg_hi:[1,0,0]
	v_pk_fma_f32 v[16:17], v[142:143], v[66:67], v[54:55] op_sel_hi:[0,1,1] neg_lo:[1,0,0] neg_hi:[1,0,0]
	v_pk_fma_f32 v[16:17], v[138:139], v[74:75], v[16:17] op_sel_hi:[0,1,1] neg_lo:[1,0,0] neg_hi:[1,0,0]
	v_pk_fma_f32 v[16:17], v[92:93], v[130:131], v[16:17] op_sel_hi:[0,1,1] neg_lo:[1,0,0] neg_hi:[1,0,0]
	v_pk_fma_f32 v[16:17], v[60:61], v[40:41], v[16:17] op_sel_hi:[0,1,1] neg_lo:[1,0,0] neg_hi:[1,0,0]
	s_waitcnt lgkmcnt(5)
	v_pk_fma_f32 v[6:7], v[68:69], v[88:89], v[6:7] op_sel_hi:[0,1,1] neg_lo:[1,0,0] neg_hi:[1,0,0]
	v_pk_fma_f32 v[16:17], v[76:77], v[46:47], v[16:17] op_sel_hi:[0,1,1] neg_lo:[1,0,0] neg_hi:[1,0,0]
	s_waitcnt lgkmcnt(3)
	v_pk_fma_f32 v[70:71], v[160:161], v[98:99], v[6:7] op_sel_hi:[0,1,1] neg_lo:[1,0,0] neg_hi:[1,0,0]
	v_mov_b32_e32 v6, v51
	v_pk_fma_f32 v[16:17], v[120:121], v[106:107], v[16:17] op_sel_hi:[0,1,1] neg_lo:[1,0,0] neg_hi:[1,0,0]
	v_pk_fma_f32 v[16:17], v[78:79], v[22:23], v[16:17] op_sel:[1,0,0] neg_lo:[1,0,0] neg_hi:[1,0,0]
	v_lshl_add_u32 v9, v6, 2, s27
	ds_read_b64 v[6:7], v9 offset:12920
	ds_read_b128 v[36:39], v9 offset:12928
	v_pk_fma_f32 v[16:17], v[126:127], v[18:19], v[16:17] op_sel_hi:[0,1,1] neg_lo:[1,0,0] neg_hi:[1,0,0]
	v_pk_fma_f32 v[16:17], v[68:69], v[90:91], v[16:17] op_sel_hi:[0,1,1] neg_lo:[1,0,0] neg_hi:[1,0,0]
	v_pk_fma_f32 v[16:17], v[160:161], v[100:101], v[16:17] op_sel_hi:[0,1,1] neg_lo:[1,0,0] neg_hi:[1,0,0]
	s_waitcnt lgkmcnt(3)
	v_fma_f32 v64, -v70, v123, v71
	v_pk_fma_f32 v[16:17], v[70:71], v[124:125], v[16:17] op_sel_hi:[0,1,1] neg_lo:[1,0,0] neg_hi:[1,0,0]
	v_mov_b32_e32 v9, v51
	s_waitcnt lgkmcnt(1)
	v_pk_fma_f32 v[66:67], v[64:65], v[6:7], v[16:17] op_sel_hi:[0,1,1] neg_lo:[1,0,0] neg_hi:[1,0,0]
	v_mov_b32_e32 v6, v51
	s_nop 0
	v_lshl_add_u32 v9, v9, 2, s27
	v_lshl_add_u32 v6, v6, 2, s27
	ds_read_b128 v[42:45], v9 offset:13056
	ds_read_b128 v[102:105], v9 offset:13072
	ds_read_b128 v[16:19], v6 offset:13216
	v_mov_b32_e32 v6, v51
	v_mov_b32_e32 v9, v2
	v_lshl_add_u32 v6, v6, 2, s27
	ds_read_b128 v[20:23], v6 offset:13360
	v_pk_fma_f32 v[6:7], v[92:93], v[56:57], v[146:147] op_sel_hi:[0,1,1] neg_lo:[1,0,0] neg_hi:[1,0,0]
	v_pk_fma_f32 v[6:7], v[60:61], v[10:11], v[6:7] op_sel_hi:[0,1,1] neg_lo:[1,0,0] neg_hi:[1,0,0]
	v_pk_fma_f32 v[6:7], v[76:77], v[8:9], v[6:7] op_sel_hi:[0,1,1] neg_lo:[1,0,0] neg_hi:[1,0,0]
	v_mov_b32_e32 v8, v15
	v_mov_b32_e32 v9, v12
	v_pk_fma_f32 v[6:7], v[120:121], v[8:9], v[6:7] op_sel_hi:[0,1,1] neg_lo:[1,0,0] neg_hi:[1,0,0]
	v_mov_b32_e32 v8, v27
	v_mov_b32_e32 v9, v24
	v_pk_fma_f32 v[6:7], v[78:79], v[8:9], v[6:7] op_sel:[1,0,0] neg_lo:[1,0,0] neg_hi:[1,0,0]
	v_mov_b32_e32 v8, v83
	v_mov_b32_e32 v9, v80
	v_pk_fma_f32 v[6:7], v[126:127], v[8:9], v[6:7] op_sel_hi:[0,1,1] neg_lo:[1,0,0] neg_hi:[1,0,0]
	v_mov_b32_e32 v8, v97
	v_mov_b32_e32 v9, v94
	v_pk_fma_f32 v[6:7], v[68:69], v[8:9], v[6:7] op_sel_hi:[0,1,1] neg_lo:[1,0,0] neg_hi:[1,0,0]
	v_mov_b32_e32 v8, v119
	v_mov_b32_e32 v9, v116
	v_pk_fma_f32 v[6:7], v[160:161], v[8:9], v[6:7] op_sel_hi:[0,1,1] neg_lo:[1,0,0] neg_hi:[1,0,0]
	v_mov_b32_e32 v8, v135
	v_mov_b32_e32 v9, v132
	v_pk_fma_f32 v[6:7], v[70:71], v[8:9], v[6:7] op_sel_hi:[0,1,1] neg_lo:[1,0,0] neg_hi:[1,0,0]
	s_waitcnt lgkmcnt(4)
	v_mov_b32_e32 v8, v39
	v_mov_b32_e32 v9, v36
	v_pk_fma_f32 v[6:7], v[64:65], v[8:9], v[6:7] op_sel_hi:[0,1,1] neg_lo:[1,0,0] neg_hi:[1,0,0]
	s_waitcnt lgkmcnt(2)
	v_mov_b32_e32 v8, v105
	v_mov_b32_e32 v9, v102
	v_fma_f32 v62, -v66, v45, v67
	v_pk_fma_f32 v[6:7], v[66:67], v[8:9], v[6:7] op_sel_hi:[0,1,1] neg_lo:[1,0,0] neg_hi:[1,0,0]
	s_waitcnt lgkmcnt(1)
; #define LAS __attribute__((address_space(3)))
; __device__ __forceinline__ unsigned cvt_pk_bf16(float lo, float hi) { unsigned r; asm volatile("v_cvt_pk_bf16_f32 %0, %1, %2" : "=v"(r) : "v"(lo), "v"(hi)); return r; }
; __device__ __forceinline__ void phase_gdn_solve(const Args& a, LAS unsigned char* lds, const WCtx& w, int l) {
;     ...
; #pragma unroll
;             for (int i = 32; i < 64; i += 4) { const f32x4 sc = *(const LAS f32x4*)(BETA + 64 * wv + i);
; #pragma unroll
;                 for (int t = 0; t < 4; ++t) x[i + t] *= sc[t]; }
; #pragma unroll
;             for (int q = 0; q < 4; ++q) { v4u o; o.x = cvt_pk_bf16(x[8 * q], x[8 * q + 1]); o.y = cvt_pk_bf16(x[8 * q + 2], x[8 * q + 3]); o.z = cvt_pk_bf16(x[8 * q + 4], x[8 * q + 5]); o.w = cvt_pk_bf16(x[8 * q + 6], x[8 * q + 7]); *(LAS v4u*)(XT + lane * TS + 8 * q) = o; }
;             f32x16 d0 = zero16(), d1 = zero16();
; #pragma unroll
;             for (int ks = 0; ks < 2; ++ks) { const bf16x8 av = *(const LAS bf16x8*)(A21 + r * TS + 8 * hh + 16 * ks);
;                 const bf16x8 b0 = *(const LAS bf16x8*)(XT + r * TS + 8 * hh + 16 * ks), b1 = *(const LAS bf16x8*)(XT + (32 + r) * TS + 8 * hh + 16 * ks);
;                 d0 = __builtin_amdgcn_mfma_f32_32x32x16_bf16(av, b0, d0, 0, 0, 0); d1 = __builtin_amdgcn_mfma_f32_32x32x16_bf16(av, b1, d1, 0, 0, 0); }
; #pragma unroll
;             for (int e = 0; e < 16; ++e) { const auto sw = __builtin_amdgcn_permlane32_swap(__float_as_uint(d0[e]), __float_as_uint(d1[e]), false, false);
;                 x[32 + 8 * (e >> 2) + (e & 3)] -= __uint_as_float(sw[0]); x[32 + 8 * (e >> 2) + 4 + (e & 3)] -= __uint_as_float(sw[1]); }
;             solve_diag(x, A22T, 32, 0, 31);
	v_mov_b32_e32 v8, v19
	v_mov_b32_e32 v9, v16
	v_pk_fma_f32 v[72:73], v[62:63], v[8:9], v[6:7] op_sel_hi:[0,1,1] neg_lo:[1,0,0] neg_hi:[1,0,0]
	v_pk_fma_f32 v[6:7], v[60:61], v[34:35], v[30:31] op_sel_hi:[0,1,1] neg_lo:[1,0,0] neg_hi:[1,0,0]
	v_mov_b32_e32 v2, v3
	v_mov_b32_e32 v3, v4
	v_pk_fma_f32 v[2:3], v[76:77], v[2:3], v[6:7] op_sel_hi:[0,1,1] neg_lo:[1,0,0] neg_hi:[1,0,0]
	v_mov_b32_e32 v4, v13
	v_pk_fma_f32 v[2:3], v[120:121], v[4:5], v[2:3] op_sel_hi:[0,1,1] neg_lo:[1,0,0] neg_hi:[1,0,0]
	v_mov_b32_e32 v4, v25
	v_mov_b32_e32 v5, v26
	v_pk_fma_f32 v[2:3], v[78:79], v[4:5], v[2:3] op_sel:[1,0,0] neg_lo:[1,0,0] neg_hi:[1,0,0]
	v_mov_b32_e32 v4, v81
	v_mov_b32_e32 v5, v82
	v_pk_fma_f32 v[2:3], v[126:127], v[4:5], v[2:3] op_sel_hi:[0,1,1] neg_lo:[1,0,0] neg_hi:[1,0,0]
	v_mov_b32_e32 v4, v95
	v_mov_b32_e32 v5, v96
	v_pk_fma_f32 v[2:3], v[68:69], v[4:5], v[2:3] op_sel_hi:[0,1,1] neg_lo:[1,0,0] neg_hi:[1,0,0]
	v_mov_b32_e32 v4, v117
	v_mov_b32_e32 v5, v118
	v_pk_fma_f32 v[2:3], v[160:161], v[4:5], v[2:3] op_sel_hi:[0,1,1] neg_lo:[1,0,0] neg_hi:[1,0,0]
	v_mov_b32_e32 v4, v133
	v_mov_b32_e32 v5, v134
	v_pk_fma_f32 v[2:3], v[70:71], v[4:5], v[2:3] op_sel_hi:[0,1,1] neg_lo:[1,0,0] neg_hi:[1,0,0]
	v_mov_b32_e32 v4, v37
	v_mov_b32_e32 v5, v38
	v_pk_fma_f32 v[2:3], v[64:65], v[4:5], v[2:3] op_sel_hi:[0,1,1] neg_lo:[1,0,0] neg_hi:[1,0,0]
	v_mov_b32_e32 v4, v103
	v_mov_b32_e32 v5, v104
	v_pk_fma_f32 v[2:3], v[66:67], v[4:5], v[2:3] op_sel_hi:[0,1,1] neg_lo:[1,0,0] neg_hi:[1,0,0]
	v_mov_b32_e32 v4, v17
	v_mov_b32_e32 v5, v18
	v_pk_fma_f32 v[2:3], v[62:63], v[4:5], v[2:3] op_sel_hi:[0,1,1] neg_lo:[1,0,0] neg_hi:[1,0,0]
	s_waitcnt lgkmcnt(0)
	v_mov_b32_e32 v4, v21
	v_mov_b32_e32 v5, v22
	v_pk_fma_f32 v[122:123], v[72:73], v[4:5], v[2:3] op_sel:[1,0,0] neg_lo:[1,0,0] neg_hi:[1,0,0]
	v_mov_b32_e32 v2, v51
	v_fma_f32 v7, -v73, v23, v72
	v_lshl_add_u32 v6, v2, 2, s27
	v_mov_b32_e32 v2, v51
	s_nop 0
	v_lshl_add_u32 v2, v2, 2, s27
	ds_read_b128 v[2:5], v2 offset:13648
	s_waitcnt lgkmcnt(0)
	ds_read_b64 v[2:3], v6 offset:13512
	v_mov_b32_e32 v6, v123
	ds_read_b128 v[80:83], v214 offset:32640
	ds_read_b128 v[88:91], v214 offset:32656
	ds_read_b128 v[52:55], v214 offset:32672
	ds_read_b128 v[56:59], v214 offset:32688
	ds_read_b128 v[42:45], v214 offset:32704
	ds_read_b128 v[46:49], v214 offset:32720
	ds_read_b128 v[34:37], v214 offset:32736
	ds_read_b128 v[38:41], v214 offset:32752
	s_waitcnt lgkmcnt(8)
	v_pk_fma_f32 v[124:125], v[122:123], v[2:3], v[6:7] op_sel_hi:[0,1,1] neg_lo:[1,0,0] neg_hi:[1,0,0]
	v_mov_b32_e32 v2, s28
	v_mad_u32_u24 v6, v197, s0, v2
	v_cvt_pk_bf16_f32 v2, v163, v156
	v_fma_f32 v96, -v124, v5, v125
	v_cvt_pk_bf16_f32 v3, v164, v152
	v_cvt_pk_bf16_f32 v4, v167, v154
	v_cvt_pk_bf16_f32 v5, v168, v158
	ds_write_b128 v6, v[2:5]
	v_cvt_pk_bf16_f32 v2, v170, v148
	v_cvt_pk_bf16_f32 v3, v172, v150
	v_cvt_pk_bf16_f32 v4, v141, v136
	v_cvt_pk_bf16_f32 v5, v142, v138
	ds_write_b128 v6, v[2:5] offset:16
	v_cvt_pk_bf16_f32 v2, v92, v60
	v_cvt_pk_bf16_f32 v3, v76, v120
	v_cvt_pk_bf16_f32 v4, v79, v126
	v_cvt_pk_bf16_f32 v5, v68, v160
	ds_write_b128 v6, v[2:5] offset:32
	v_cvt_pk_bf16_f32 v2, v70, v64
	v_cvt_pk_bf16_f32 v3, v66, v62
	v_cvt_pk_bf16_f32 v4, v73, v122
	v_cvt_pk_bf16_f32 v5, v124, v96
	ds_write_b128 v6, v[2:5] offset:48
	v_mul_u32_u24_e32 v2, 0x48, v213
	v_lshlrev_b32_e32 v2, 1, v2
	v_lshlrev_b32_e32 v3, 4, v199
	v_add3_u32 v4, s27, v2, v3
	v_add3_u32 v61, s28, v2, v3
	ds_read_b128 v[18:21], v61 offset:4608
	ds_read_b128 v[22:25], v4 offset:18432
	ds_read_b128 v[98:101], v4 offset:18464
	ds_read_b128 v[2:5], v61
	ds_read_b128 v[102:105], v61 offset:32
	s_waitcnt lgkmcnt(1)
	v_mfma_f32_32x32x16_bf16 v[2:17], v[22:25], v[2:5], 0
	ds_read_b128 v[116:119], v61 offset:4640
	s_add_i32 s0, s69, s68
	s_ashr_i32 s1, s0, 31
	s_lshl_b64 s[0:1], s[0:1], 13
	v_mfma_f32_32x32x16_bf16 v[18:33], v[22:25], v[18:21], 0
	s_waitcnt lgkmcnt(1)
	v_mfma_f32_32x32x16_bf16 v[2:17], v[98:101], v[102:105], v[2:17]
	s_waitcnt lgkmcnt(0)
	v_mfma_f32_32x32x16_bf16 v[18:33], v[98:101], v[116:119], v[18:33]
	s_nop 11
	v_permlane32_swap_b32_e32 v2, v18
	v_permlane32_swap_b32_e32 v3, v19
	v_permlane32_swap_b32_e32 v4, v20
	v_permlane32_swap_b32_e32 v5, v21
	v_permlane32_swap_b32_e32 v6, v22
	v_permlane32_swap_b32_e32 v7, v23
	v_permlane32_swap_b32_e32 v8, v24
	v_permlane32_swap_b32_e32 v9, v25
	v_permlane32_swap_b32_e32 v10, v26
	v_permlane32_swap_b32_e32 v11, v27
	v_permlane32_swap_b32_e32 v12, v28
	v_permlane32_swap_b32_e32 v13, v29
	v_permlane32_swap_b32_e32 v14, v30
	v_permlane32_swap_b32_e32 v15, v31
	v_permlane32_swap_b32_e32 v16, v32
	v_permlane32_swap_b32_e32 v17, v33
	v_fma_f32 v2, v80, v63, -v2
	v_fma_f32 v61, v88, v111, -v18
	v_fma_f32 v63, v89, v112, -v19
	v_fma_f32 v65, v82, v87, -v4
	v_fma_f32 v67, v83, v108, -v5
	v_fma_f32 v52, v52, v149, -v6
	v_fma_f32 v53, v53, v151, -v7
	v_fma_f32 v54, v54, v153, -v8
	v_fma_f32 v55, v55, v159, -v9
	v_fma_f32 v42, v42, v190, -v10
	v_fma_f32 v43, v43, v191, -v11
	v_fma_f32 v44, v44, v192, -v12
	v_fma_f32 v45, v45, v193, -v13
	v_fma_f32 v34, v34, v202, -v14
	v_fma_f32 v35, v35, v203, -v15
	v_fma_f32 v36, v36, v204, -v16
	v_fma_f32 v37, v37, v205, -v17
	ds_read_b128 v[4:7], v157 offset:13824
	ds_read_b128 v[8:11], v157 offset:13840
	ds_read_b128 v[12:15], v157 offset:13856
	ds_read_b128 v[16:19], v157 offset:13872
	v_fma_f32 v3, v81, v84, -v3
	v_fma_f32 v30, v38, v206, -v30
	v_fma_f32 v31, v39, v207, -v31
	s_waitcnt lgkmcnt(3)
	v_fma_f32 v3, -v2, v5, v3
	v_fma_f32 v38, -v2, v6, v65
	v_fma_f32 v39, -v2, v7, v67
	ds_read_b128 v[4:7], v157 offset:13888
	v_fma_f32 v20, v90, v115, -v20
	v_fma_f32 v21, v91, v139, -v21
	v_fma_f32 v22, v56, v162, -v22
	v_fma_f32 v23, v57, v165, -v23
	s_waitcnt lgkmcnt(3)
; #define LAS __attribute__((address_space(3)))
; __device__ __forceinline__ void solve_diag(float (&x)[64], const LAS float* AT, const int o, const int ja, const int jb) {
; #pragma unroll
;     for (int j = ja; j < jb; ++j) { const float xj = x[o + j];
;         int z = 0; if (j >= 2) asm("" : "+v"(z) : "v"(x[o + j - 2]));
;         const LAS float* ATj = AT + z;
; #pragma unroll
;         for (int i4 = ((j + 1) >> 2) << 2; i4 < 32; i4 += 4) { const f32x4 av = *(const LAS f32x4*)(ATj + j * 36 + i4);
; #pragma unroll
;             for (int t = 0; t < 4; ++t) if (i4 + t > j) x[o + i4 + t] -= av[t] * xj; } }
; __device__ __forceinline__ void phase_gdn_solve(const Args& a, LAS unsigned char* lds, const WCtx& w, int l) {
;     ...
;             solve_diag(x, A22T, 32, 0, 31);
	v_fma_f32 v10, -v2, v10, v20
	v_fma_f32 v11, -v2, v11, v21
	s_waitcnt lgkmcnt(1)
	v_fma_f32 v16, -v2, v16, v22
	v_fma_f32 v17, -v2, v17, v23
	s_waitcnt lgkmcnt(0)
	v_fma_f32 v20, -v2, v4, v42
	v_fma_f32 v21, -v2, v5, v43
	v_fma_f32 v22, -v2, v6, v44
	v_fma_f32 v23, -v2, v7, v45
	ds_read_b128 v[4:7], v157 offset:13904
	v_fma_f32 v24, v58, v188, -v24
	v_fma_f32 v25, v59, v189, -v25
	v_fma_f32 v26, v46, v194, -v26
	v_fma_f32 v27, v47, v195, -v27
	v_fma_f32 v28, v48, v200, -v28
	v_fma_f32 v29, v49, v201, -v29
	v_fma_f32 v18, -v2, v18, v24
	v_fma_f32 v19, -v2, v19, v25
	s_waitcnt lgkmcnt(0)
	v_fma_f32 v24, -v2, v4, v26
	v_fma_f32 v25, -v2, v5, v27
	v_fma_f32 v26, -v2, v6, v28
	v_fma_f32 v27, -v2, v7, v29
	ds_read_b128 v[4:7], v157 offset:13920
	v_fma_f32 v32, v40, v208, -v32
	v_fma_f32 v33, v41, v209, -v33
	v_fma_f32 v40, -v2, v8, v61
	v_fma_f32 v41, -v2, v9, v63
	s_waitcnt lgkmcnt(0)
	v_fma_f32 v28, -v2, v4, v34
	v_fma_f32 v29, -v2, v5, v35
	v_fma_f32 v34, -v2, v6, v36
	v_fma_f32 v35, -v2, v7, v37
	ds_read_b128 v[4:7], v157 offset:13936
	v_fma_f32 v12, -v2, v12, v52
	v_fma_f32 v13, -v2, v13, v53
	v_fma_f32 v14, -v2, v14, v54
	v_fma_f32 v15, -v2, v15, v55
	s_waitcnt lgkmcnt(0)
	v_fma_f32 v30, -v2, v4, v30
	v_fma_f32 v31, -v2, v5, v31
	v_fma_f32 v32, -v2, v6, v32
	v_fma_f32 v33, -v2, v7, v33
	ds_read_b128 v[4:7], v157 offset:13968
	s_waitcnt lgkmcnt(0)
	v_fma_f32 v4, -v3, v6, v38
	v_fma_f32 v5, -v3, v7, v39
	ds_read_b128 v[6:9], v157 offset:13984
	s_waitcnt lgkmcnt(0)
	v_fma_f32 v36, -v3, v6, v40
	v_fma_f32 v37, -v3, v7, v41
	v_fma_f32 v38, -v3, v8, v10
	v_fma_f32 v39, -v3, v9, v11
	ds_read_b128 v[6:9], v157 offset:14000
	s_waitcnt lgkmcnt(0)
	v_fma_f32 v40, -v3, v6, v12
	v_fma_f32 v41, -v3, v7, v13
	v_fma_f32 v42, -v3, v8, v14
	v_fma_f32 v43, -v3, v9, v15
	ds_read_b128 v[6:9], v157 offset:14016
	s_waitcnt lgkmcnt(0)
	v_fma_f32 v44, -v3, v6, v16
	v_fma_f32 v45, -v3, v7, v17
	v_fma_f32 v46, -v3, v8, v18
	v_fma_f32 v47, -v3, v9, v19
	ds_read_b128 v[6:9], v157 offset:14032
	s_waitcnt lgkmcnt(0)
	v_fma_f32 v48, -v3, v6, v20
	v_fma_f32 v49, -v3, v7, v21
	v_fma_f32 v22, -v3, v8, v22
	v_fma_f32 v23, -v3, v9, v23
	ds_read_b128 v[6:9], v157 offset:14048
	s_waitcnt lgkmcnt(0)
	v_fma_f32 v24, -v3, v6, v24
	v_fma_f32 v25, -v3, v7, v25
	v_fma_f32 v26, -v3, v8, v26
	v_fma_f32 v27, -v3, v9, v27
	ds_read_b128 v[6:9], v157 offset:14064
	s_waitcnt lgkmcnt(0)
	v_fma_f32 v28, -v3, v6, v28
	v_fma_f32 v29, -v3, v7, v29
	v_fma_f32 v34, -v3, v8, v34
	v_fma_f32 v35, -v3, v9, v35
	ds_read_b128 v[6:9], v157 offset:14080
	s_waitcnt lgkmcnt(0)
	v_fma_f32 v30, -v3, v6, v30
	v_mov_b32_e32 v6, v51
	v_fma_f32 v31, -v3, v7, v31
	v_lshl_add_u32 v52, v6, 2, s27
	v_fma_f32 v32, -v3, v8, v32
	v_fma_f32 v33, -v3, v9, v33
	ds_read_b128 v[6:9], v52 offset:14112
	ds_read_b128 v[10:13], v52 offset:14128
	ds_read_b128 v[14:17], v52 offset:14144
	ds_read_b128 v[18:21], v52 offset:14160
	s_waitcnt lgkmcnt(3)
	v_fma_f32 v5, -v4, v9, v5
	ds_read_b128 v[6:9], v52 offset:14176
	s_waitcnt lgkmcnt(3)
	v_fma_f32 v36, -v4, v10, v36
	v_fma_f32 v37, -v4, v11, v37
	v_fma_f32 v38, -v4, v12, v38
	v_fma_f32 v39, -v4, v13, v39
	s_waitcnt lgkmcnt(0)
	v_fma_f32 v48, -v4, v6, v48
	v_fma_f32 v49, -v4, v7, v49
	v_fma_f32 v22, -v4, v8, v22
	v_fma_f32 v23, -v4, v9, v23
	ds_read_b128 v[6:9], v52 offset:14192
	v_fma_f32 v40, -v4, v14, v40
	v_fma_f32 v41, -v4, v15, v41
	v_fma_f32 v42, -v4, v16, v42
	v_fma_f32 v43, -v4, v17, v43
	s_waitcnt lgkmcnt(0)
	v_fma_f32 v24, -v4, v6, v24
	v_fma_f32 v25, -v4, v7, v25
	v_fma_f32 v26, -v4, v8, v26
	v_fma_f32 v27, -v4, v9, v27
	ds_read_b128 v[6:9], v52 offset:14208
	v_fma_f32 v44, -v4, v18, v44
	v_fma_f32 v45, -v4, v19, v45
	v_fma_f32 v46, -v4, v20, v46
	v_fma_f32 v47, -v4, v21, v47
	s_waitcnt lgkmcnt(0)
	v_fma_f32 v28, -v4, v6, v28
	v_fma_f32 v29, -v4, v7, v29
	v_fma_f32 v34, -v4, v8, v34
	v_fma_f32 v35, -v4, v9, v35
	ds_read_b128 v[6:9], v52 offset:14224
	s_waitcnt lgkmcnt(0)
	v_fma_f32 v30, -v4, v6, v30
	v_mov_b32_e32 v6, v51
	v_fma_f32 v31, -v4, v7, v31
	v_lshl_add_u32 v52, v6, 2, s27
	v_fma_f32 v32, -v4, v8, v32
	v_fma_f32 v33, -v4, v9, v33
	ds_read_b128 v[6:9], v52 offset:14272
	ds_read_b128 v[10:13], v52 offset:14288
	ds_read_b128 v[14:17], v52 offset:14304
	ds_read_b128 v[18:21], v52 offset:14320
	s_waitcnt lgkmcnt(3)
	v_fma_f32 v6, -v5, v6, v36
	v_fma_f32 v7, -v5, v7, v37
	v_fma_f32 v36, -v5, v8, v38
	v_fma_f32 v37, -v5, v9, v39
	s_waitcnt lgkmcnt(2)
	v_fma_f32 v38, -v5, v10, v40
	v_fma_f32 v39, -v5, v11, v41
	ds_read_b128 v[8:11], v52 offset:14336
	v_fma_f32 v40, -v5, v12, v42
	v_fma_f32 v41, -v5, v13, v43
	s_waitcnt lgkmcnt(2)
	v_fma_f32 v42, -v5, v14, v44
	v_fma_f32 v43, -v5, v15, v45
	s_waitcnt lgkmcnt(0)
	v_fma_f32 v24, -v5, v8, v24
	v_fma_f32 v25, -v5, v9, v25
	v_fma_f32 v26, -v5, v10, v26
	v_fma_f32 v27, -v5, v11, v27
	ds_read_b128 v[8:11], v52 offset:14352
	v_fma_f32 v44, -v5, v16, v46
	v_fma_f32 v45, -v5, v17, v47
	v_fma_f32 v46, -v5, v18, v48
	v_fma_f32 v47, -v5, v19, v49
	s_waitcnt lgkmcnt(0)
	v_fma_f32 v28, -v5, v8, v28
	v_fma_f32 v29, -v5, v9, v29
	v_fma_f32 v34, -v5, v10, v34
	v_fma_f32 v35, -v5, v11, v35
	ds_read_b128 v[8:11], v52 offset:14368
	v_fma_f32 v48, -v5, v20, v22
	v_fma_f32 v49, -v5, v21, v23
	s_waitcnt lgkmcnt(0)
	v_fma_f32 v30, -v5, v8, v30
	v_mov_b32_e32 v8, v51
	v_fma_f32 v31, -v5, v9, v31
	v_lshl_add_u32 v52, v8, 2, s27
	v_fma_f32 v32, -v5, v10, v32
	v_fma_f32 v33, -v5, v11, v33
	ds_read_b128 v[8:11], v52 offset:14416
	ds_read_b128 v[12:15], v52 offset:14432
	ds_read_b128 v[16:19], v52 offset:14448
	ds_read_b128 v[20:23], v52 offset:14464
	s_waitcnt lgkmcnt(3)
	v_fma_f32 v7, -v6, v9, v7
	v_fma_f32 v36, -v6, v10, v36
	v_fma_f32 v37, -v6, v11, v37
	ds_read_b128 v[8:11], v52 offset:14480
	s_waitcnt lgkmcnt(3)
; #define LAS __attribute__((address_space(3)))
; __device__ __forceinline__ void solve_diag(float (&x)[64], const LAS float* AT, const int o, const int ja, const int jb) {
; #pragma unroll
;     for (int j = ja; j < jb; ++j) { const float xj = x[o + j];
;         int z = 0; if (j >= 2) asm("" : "+v"(z) : "v"(x[o + j - 2]));
;         const LAS float* ATj = AT + z;
; #pragma unroll
;         for (int i4 = ((j + 1) >> 2) << 2; i4 < 32; i4 += 4) { const f32x4 av = *(const LAS f32x4*)(ATj + j * 36 + i4);
; #pragma unroll
;             for (int t = 0; t < 4; ++t) if (i4 + t > j) x[o + i4 + t] -= av[t] * xj; } }
; __device__ __forceinline__ void phase_gdn_solve(const Args& a, LAS unsigned char* lds, const WCtx& w, int l) {
;     ...
;             solve_diag(x, A22T, 32, 0, 31);
	v_fma_f32 v38, -v6, v12, v38
	v_fma_f32 v39, -v6, v13, v39
	v_fma_f32 v40, -v6, v14, v40
	v_fma_f32 v41, -v6, v15, v41
	s_waitcnt lgkmcnt(0)
	v_fma_f32 v24, -v6, v8, v24
	v_fma_f32 v25, -v6, v9, v25
	v_fma_f32 v26, -v6, v10, v26
	v_fma_f32 v27, -v6, v11, v27
	ds_read_b128 v[8:11], v52 offset:14496
	v_fma_f32 v42, -v6, v16, v42
	v_fma_f32 v43, -v6, v17, v43
	v_fma_f32 v44, -v6, v18, v44
	v_fma_f32 v45, -v6, v19, v45
	s_waitcnt lgkmcnt(0)
	v_fma_f32 v28, -v6, v8, v28
	v_fma_f32 v29, -v6, v9, v29
	v_fma_f32 v34, -v6, v10, v34
	v_fma_f32 v35, -v6, v11, v35
	ds_read_b128 v[8:11], v52 offset:14512
	v_fma_f32 v46, -v6, v20, v46
	v_fma_f32 v47, -v6, v21, v47
	v_fma_f32 v48, -v6, v22, v48
	v_fma_f32 v49, -v6, v23, v49
	s_waitcnt lgkmcnt(0)
	v_fma_f32 v30, -v6, v8, v30
	v_mov_b32_e32 v8, v51
	v_fma_f32 v31, -v6, v9, v31
	v_lshl_add_u32 v52, v8, 2, s27
	v_fma_f32 v32, -v6, v10, v32
	v_fma_f32 v33, -v6, v11, v33
	ds_read_b128 v[8:11], v52 offset:14560
	ds_read_b128 v[12:15], v52 offset:14576
	ds_read_b128 v[16:19], v52 offset:14592
	ds_read_b128 v[20:23], v52 offset:14608
	s_waitcnt lgkmcnt(3)
	v_fma_f32 v8, -v7, v10, v36
	v_fma_f32 v9, -v7, v11, v37
	s_waitcnt lgkmcnt(2)
	v_fma_f32 v36, -v7, v12, v38
	v_fma_f32 v37, -v7, v13, v39
	ds_read_b128 v[10:13], v52 offset:14624
	v_fma_f32 v38, -v7, v14, v40
	v_fma_f32 v39, -v7, v15, v41
	s_waitcnt lgkmcnt(2)
	v_fma_f32 v40, -v7, v16, v42
	v_fma_f32 v41, -v7, v17, v43
	v_fma_f32 v42, -v7, v18, v44
	v_fma_f32 v43, -v7, v19, v45
	s_waitcnt lgkmcnt(1)
	v_fma_f32 v44, -v7, v20, v46
	v_fma_f32 v45, -v7, v21, v47
	v_fma_f32 v46, -v7, v22, v48
	v_fma_f32 v47, -v7, v23, v49
	s_waitcnt lgkmcnt(0)
	v_fma_f32 v48, -v7, v10, v24
	v_fma_f32 v49, -v7, v11, v25
	v_fma_f32 v26, -v7, v12, v26
	v_fma_f32 v27, -v7, v13, v27
	ds_read_b128 v[10:13], v52 offset:14640
	s_waitcnt lgkmcnt(0)
	v_fma_f32 v28, -v7, v10, v28
	v_fma_f32 v29, -v7, v11, v29
	v_fma_f32 v34, -v7, v12, v34
	v_fma_f32 v35, -v7, v13, v35
	ds_read_b128 v[10:13], v52 offset:14656
	s_waitcnt lgkmcnt(0)
	v_fma_f32 v30, -v7, v10, v30
	v_mov_b32_e32 v10, v51
	v_fma_f32 v31, -v7, v11, v31
	v_lshl_add_u32 v52, v10, 2, s27
	v_fma_f32 v32, -v7, v12, v32
	v_fma_f32 v33, -v7, v13, v33
	ds_read_b128 v[10:13], v52 offset:14704
	ds_read_b128 v[14:17], v52 offset:14720
	ds_read_b128 v[18:21], v52 offset:14736
	ds_read_b128 v[22:25], v52 offset:14752
	s_waitcnt lgkmcnt(3)
	v_fma_f32 v9, -v8, v13, v9
	ds_read_b128 v[10:13], v52 offset:14768
	s_waitcnt lgkmcnt(3)
	v_fma_f32 v36, -v8, v14, v36
	v_fma_f32 v37, -v8, v15, v37
	v_fma_f32 v38, -v8, v16, v38
	v_fma_f32 v39, -v8, v17, v39
	s_waitcnt lgkmcnt(0)
	v_fma_f32 v48, -v8, v10, v48
	v_fma_f32 v49, -v8, v11, v49
	v_fma_f32 v26, -v8, v12, v26
	v_fma_f32 v27, -v8, v13, v27
	ds_read_b128 v[10:13], v52 offset:14784
	v_fma_f32 v40, -v8, v18, v40
	v_fma_f32 v41, -v8, v19, v41
	v_fma_f32 v42, -v8, v20, v42
	v_fma_f32 v43, -v8, v21, v43
	s_waitcnt lgkmcnt(0)
	v_fma_f32 v28, -v8, v10, v28
	v_fma_f32 v29, -v8, v11, v29
	v_fma_f32 v34, -v8, v12, v34
	v_fma_f32 v35, -v8, v13, v35
	ds_read_b128 v[10:13], v52 offset:14800
	v_fma_f32 v44, -v8, v22, v44
	v_fma_f32 v45, -v8, v23, v45
	v_fma_f32 v46, -v8, v24, v46
	v_fma_f32 v47, -v8, v25, v47
	s_waitcnt lgkmcnt(0)
	v_fma_f32 v30, -v8, v10, v30
	v_mov_b32_e32 v10, v51
	v_fma_f32 v31, -v8, v11, v31
	v_lshl_add_u32 v52, v10, 2, s27
	v_fma_f32 v32, -v8, v12, v32
	v_fma_f32 v33, -v8, v13, v33
	ds_read_b128 v[10:13], v52 offset:14864
	ds_read_b128 v[14:17], v52 offset:14880
	ds_read_b128 v[18:21], v52 offset:14896
	ds_read_b128 v[22:25], v52 offset:14912
	s_waitcnt lgkmcnt(3)
	v_fma_f32 v10, -v9, v10, v36
	v_fma_f32 v11, -v9, v11, v37
	v_fma_f32 v36, -v9, v12, v38
	v_fma_f32 v37, -v9, v13, v39
	s_waitcnt lgkmcnt(2)
	v_fma_f32 v38, -v9, v14, v40
	v_fma_f32 v39, -v9, v15, v41
	ds_read_b128 v[12:15], v52 offset:14928
	v_fma_f32 v40, -v9, v16, v42
	v_fma_f32 v41, -v9, v17, v43
	s_waitcnt lgkmcnt(2)
	v_fma_f32 v42, -v9, v18, v44
	v_fma_f32 v43, -v9, v19, v45
	s_waitcnt lgkmcnt(0)
	v_fma_f32 v28, -v9, v12, v28
	v_fma_f32 v29, -v9, v13, v29
	v_fma_f32 v34, -v9, v14, v34
	v_fma_f32 v35, -v9, v15, v35
	ds_read_b128 v[12:15], v52 offset:14944
	v_fma_f32 v44, -v9, v20, v46
	v_fma_f32 v45, -v9, v21, v47
	v_fma_f32 v46, -v9, v22, v48
	v_fma_f32 v47, -v9, v23, v49
	s_waitcnt lgkmcnt(0)
	v_fma_f32 v30, -v9, v12, v30
	v_mov_b32_e32 v12, v51
	v_fma_f32 v48, -v9, v24, v26
	v_lshl_add_u32 v52, v12, 2, s27
	v_fma_f32 v49, -v9, v25, v27
	v_fma_f32 v31, -v9, v13, v31
	v_fma_f32 v32, -v9, v14, v32
	v_fma_f32 v33, -v9, v15, v33
	ds_read_b128 v[12:15], v52 offset:15008
	ds_read_b128 v[16:19], v52 offset:15024
	ds_read_b128 v[20:23], v52 offset:15040
	ds_read_b128 v[24:27], v52 offset:15056
	s_waitcnt lgkmcnt(3)
	v_fma_f32 v11, -v10, v13, v11
	v_fma_f32 v36, -v10, v14, v36
	v_fma_f32 v37, -v10, v15, v37
	ds_read_b128 v[12:15], v52 offset:15072
	s_waitcnt lgkmcnt(3)
	v_fma_f32 v38, -v10, v16, v38
	v_fma_f32 v39, -v10, v17, v39
	v_fma_f32 v40, -v10, v18, v40
	v_fma_f32 v41, -v10, v19, v41
	s_waitcnt lgkmcnt(0)
	v_fma_f32 v28, -v10, v12, v28
	v_fma_f32 v29, -v10, v13, v29
	v_fma_f32 v34, -v10, v14, v34
	v_fma_f32 v35, -v10, v15, v35
	ds_read_b128 v[12:15], v52 offset:15088
	v_fma_f32 v42, -v10, v20, v42
	v_fma_f32 v43, -v10, v21, v43
	v_fma_f32 v44, -v10, v22, v44
	v_fma_f32 v45, -v10, v23, v45
	s_waitcnt lgkmcnt(0)
	v_fma_f32 v30, -v10, v12, v30
	v_mov_b32_e32 v12, v51
	v_fma_f32 v46, -v10, v24, v46
	v_lshl_add_u32 v52, v12, 2, s27
	v_fma_f32 v47, -v10, v25, v47
	v_fma_f32 v48, -v10, v26, v48
	v_fma_f32 v49, -v10, v27, v49
	v_fma_f32 v31, -v10, v13, v31
	v_fma_f32 v32, -v10, v14, v32
	v_fma_f32 v33, -v10, v15, v33
	ds_read_b128 v[12:15], v52 offset:15152
	ds_read_b128 v[16:19], v52 offset:15168
	ds_read_b128 v[20:23], v52 offset:15184
	ds_read_b128 v[24:27], v52 offset:15200
	s_waitcnt lgkmcnt(3)
; #define LAS __attribute__((address_space(3)))
; __device__ __forceinline__ void solve_diag(float (&x)[64], const LAS float* AT, const int o, const int ja, const int jb) {
; #pragma unroll
;     for (int j = ja; j < jb; ++j) { const float xj = x[o + j];
;         int z = 0; if (j >= 2) asm("" : "+v"(z) : "v"(x[o + j - 2]));
;         const LAS float* ATj = AT + z;
; #pragma unroll
;         for (int i4 = ((j + 1) >> 2) << 2; i4 < 32; i4 += 4) { const f32x4 av = *(const LAS f32x4*)(ATj + j * 36 + i4);
; #pragma unroll
;             for (int t = 0; t < 4; ++t) if (i4 + t > j) x[o + i4 + t] -= av[t] * xj; } }
; __device__ __forceinline__ void phase_gdn_solve(const Args& a, LAS unsigned char* lds, const WCtx& w, int l) {
;     ...
;             solve_diag(x, A22T, 32, 0, 31);
	v_fma_f32 v12, -v11, v14, v36
	v_fma_f32 v13, -v11, v15, v37
	s_waitcnt lgkmcnt(2)
	v_fma_f32 v36, -v11, v16, v38
	v_fma_f32 v37, -v11, v17, v39
	ds_read_b128 v[14:17], v52 offset:15216
	v_fma_f32 v38, -v11, v18, v40
	v_fma_f32 v39, -v11, v19, v41
	s_waitcnt lgkmcnt(2)
	v_fma_f32 v40, -v11, v20, v42
	v_fma_f32 v41, -v11, v21, v43
	v_fma_f32 v42, -v11, v22, v44
	v_fma_f32 v43, -v11, v23, v45
	s_waitcnt lgkmcnt(1)
	v_fma_f32 v44, -v11, v24, v46
	v_fma_f32 v45, -v11, v25, v47
	v_fma_f32 v46, -v11, v26, v48
	v_fma_f32 v47, -v11, v27, v49
	s_waitcnt lgkmcnt(0)
	v_fma_f32 v48, -v11, v14, v28
	v_fma_f32 v49, -v11, v15, v29
	v_fma_f32 v34, -v11, v16, v34
	v_fma_f32 v35, -v11, v17, v35
	ds_read_b128 v[14:17], v52 offset:15232
	s_waitcnt lgkmcnt(0)
	v_fma_f32 v30, -v11, v14, v30
	v_mov_b32_e32 v14, v51
	v_fma_f32 v31, -v11, v15, v31
	v_lshl_add_u32 v52, v14, 2, s27
	v_fma_f32 v32, -v11, v16, v32
	v_fma_f32 v33, -v11, v17, v33
	ds_read_b128 v[14:17], v52 offset:15296
	ds_read_b128 v[18:21], v52 offset:15312
	ds_read_b128 v[22:25], v52 offset:15328
	ds_read_b128 v[26:29], v52 offset:15344
	s_waitcnt lgkmcnt(3)
	v_fma_f32 v13, -v12, v17, v13
	ds_read_b128 v[14:17], v52 offset:15360
	s_waitcnt lgkmcnt(3)
	v_fma_f32 v36, -v12, v18, v36
	v_fma_f32 v37, -v12, v19, v37
	v_fma_f32 v38, -v12, v20, v38
	v_fma_f32 v39, -v12, v21, v39
	s_waitcnt lgkmcnt(0)
	v_fma_f32 v48, -v12, v14, v48
	v_fma_f32 v49, -v12, v15, v49
	v_fma_f32 v34, -v12, v16, v34
	v_fma_f32 v35, -v12, v17, v35
	ds_read_b128 v[14:17], v52 offset:15376
	v_fma_f32 v40, -v12, v22, v40
	v_fma_f32 v41, -v12, v23, v41
	v_fma_f32 v42, -v12, v24, v42
	v_fma_f32 v43, -v12, v25, v43
	s_waitcnt lgkmcnt(0)
	v_fma_f32 v30, -v12, v14, v30
	v_mov_b32_e32 v14, v51
	v_fma_f32 v44, -v12, v26, v44
	v_lshl_add_u32 v52, v14, 2, s27
	v_fma_f32 v45, -v12, v27, v45
	v_fma_f32 v46, -v12, v28, v46
	v_fma_f32 v47, -v12, v29, v47
	v_fma_f32 v31, -v12, v15, v31
	v_fma_f32 v32, -v12, v16, v32
	v_fma_f32 v33, -v12, v17, v33
	ds_read_b128 v[14:17], v52 offset:15456
	ds_read_b128 v[18:21], v52 offset:15472
	ds_read_b128 v[22:25], v52 offset:15488
	ds_read_b128 v[26:29], v52 offset:15504
	s_waitcnt lgkmcnt(3)
	v_fma_f32 v14, -v13, v14, v36
	v_fma_f32 v15, -v13, v15, v37
	v_fma_f32 v36, -v13, v16, v38
	v_fma_f32 v37, -v13, v17, v39
	s_waitcnt lgkmcnt(2)
	v_fma_f32 v38, -v13, v18, v40
	v_fma_f32 v39, -v13, v19, v41
	ds_read_b128 v[16:19], v52 offset:15520
	v_fma_f32 v40, -v13, v20, v42
	s_waitcnt lgkmcnt(2)
	v_fma_f32 v42, -v13, v22, v44
	v_fma_f32 v44, -v13, v24, v46
	s_waitcnt lgkmcnt(1)
	v_fma_f32 v46, -v13, v26, v48
	s_waitcnt lgkmcnt(0)
	v_fma_f32 v48, -v13, v16, v30
	v_mov_b32_e32 v16, v51
	v_fma_f32 v41, -v13, v21, v43
	v_lshl_add_u32 v52, v16, 2, s27
	v_fma_f32 v43, -v13, v23, v45
	v_fma_f32 v45, -v13, v25, v47
	v_fma_f32 v47, -v13, v27, v49
	v_fma_f32 v34, -v13, v28, v34
	v_fma_f32 v35, -v13, v29, v35
	v_fma_f32 v49, -v13, v17, v31
	v_fma_f32 v32, -v13, v18, v32
	v_fma_f32 v33, -v13, v19, v33
	ds_read_b128 v[16:19], v52 offset:15600
	ds_read_b128 v[20:23], v52 offset:15616
	ds_read_b128 v[24:27], v52 offset:15632
	ds_read_b128 v[28:31], v52 offset:15648
	s_waitcnt lgkmcnt(3)
	v_fma_f32 v15, -v14, v17, v15
	v_fma_f32 v36, -v14, v18, v36
	v_fma_f32 v37, -v14, v19, v37
	ds_read_b128 v[16:19], v52 offset:15664
	s_waitcnt lgkmcnt(3)
	v_fma_f32 v38, -v14, v20, v38
	v_fma_f32 v39, -v14, v21, v39
	v_fma_f32 v40, -v14, v22, v40
	v_fma_f32 v41, -v14, v23, v41
	s_waitcnt lgkmcnt(0)
	v_fma_f32 v48, -v14, v16, v48
	v_mov_b32_e32 v16, v51
	v_fma_f32 v42, -v14, v24, v42
	v_lshl_add_u32 v52, v16, 2, s27
	v_fma_f32 v43, -v14, v25, v43
	v_fma_f32 v44, -v14, v26, v44
	v_fma_f32 v45, -v14, v27, v45
	v_fma_f32 v46, -v14, v28, v46
	v_fma_f32 v47, -v14, v29, v47
	v_fma_f32 v34, -v14, v30, v34
	v_fma_f32 v35, -v14, v31, v35
	v_fma_f32 v49, -v14, v17, v49
	v_fma_f32 v32, -v14, v18, v32
	v_fma_f32 v33, -v14, v19, v33
	ds_read_b128 v[16:19], v52 offset:15744
	ds_read_b128 v[20:23], v52 offset:15760
	ds_read_b128 v[24:27], v52 offset:15776
	ds_read_b128 v[28:31], v52 offset:15792
	s_waitcnt lgkmcnt(3)
	v_fma_f32 v16, -v15, v18, v36
	v_fma_f32 v17, -v15, v19, v37
	s_waitcnt lgkmcnt(2)
	v_fma_f32 v36, -v15, v20, v38
	v_fma_f32 v37, -v15, v21, v39
	ds_read_b128 v[18:21], v52 offset:15808
	v_fma_f32 v38, -v15, v22, v40
	s_waitcnt lgkmcnt(2)
	v_fma_f32 v40, -v15, v24, v42
	v_fma_f32 v42, -v15, v26, v44
	s_waitcnt lgkmcnt(1)
	v_fma_f32 v44, -v15, v28, v46
	s_waitcnt lgkmcnt(0)
	v_fma_f32 v46, -v15, v18, v48
	v_mov_b32_e32 v18, v51
	v_fma_f32 v39, -v15, v23, v41
	v_lshl_add_u32 v52, v18, 2, s27
	v_fma_f32 v41, -v15, v25, v43
	v_fma_f32 v43, -v15, v27, v45
	v_fma_f32 v45, -v15, v29, v47
	v_fma_f32 v34, -v15, v30, v34
	v_fma_f32 v35, -v15, v31, v35
	v_fma_f32 v47, -v15, v19, v49
	v_fma_f32 v48, -v15, v20, v32
	v_fma_f32 v49, -v15, v21, v33
	ds_read_b128 v[18:21], v52 offset:15888
	ds_read_b128 v[22:25], v52 offset:15904
	ds_read_b128 v[26:29], v52 offset:15920
	ds_read_b128 v[30:33], v52 offset:15936
	s_waitcnt lgkmcnt(3)
	v_fma_f32 v17, -v16, v21, v17
	ds_read_b128 v[18:21], v52 offset:15952
	s_waitcnt lgkmcnt(3)
	v_fma_f32 v24, -v16, v24, v38
	s_waitcnt lgkmcnt(1)
	v_fma_f32 v32, -v16, v32, v34
	v_fma_f32 v22, -v16, v22, v36
	v_fma_f32 v23, -v16, v23, v37
	s_waitcnt lgkmcnt(0)
	v_fma_f32 v34, -v16, v18, v46
	v_mov_b32_e32 v18, v51
	v_fma_f32 v33, -v16, v33, v35
	v_lshl_add_u32 v38, v18, 2, s27
	v_fma_f32 v35, -v16, v19, v47
	v_fma_f32 v36, -v16, v20, v48
	v_fma_f32 v37, -v16, v21, v49
	ds_read_b128 v[18:21], v38 offset:16048
	v_fma_f32 v25, -v16, v25, v39
	v_fma_f32 v26, -v16, v26, v40
	v_fma_f32 v27, -v16, v27, v41
	v_fma_f32 v28, -v16, v28, v42
	s_waitcnt lgkmcnt(0)
; #define LAS __attribute__((address_space(3)))
; __device__ __forceinline__ void solve_diag(float (&x)[64], const LAS float* AT, const int o, const int ja, const int jb) {
; #pragma unroll
;     for (int j = ja; j < jb; ++j) { const float xj = x[o + j];
;         int z = 0; if (j >= 2) asm("" : "+v"(z) : "v"(x[o + j - 2]));
;         const LAS float* ATj = AT + z;
; #pragma unroll
;         for (int i4 = ((j + 1) >> 2) << 2; i4 < 32; i4 += 4) { const f32x4 av = *(const LAS f32x4*)(ATj + j * 36 + i4);
; #pragma unroll
;             for (int t = 0; t < 4; ++t) if (i4 + t > j) x[o + i4 + t] -= av[t] * xj; } }
; __device__ __forceinline__ void phase_gdn_solve(const Args& a, LAS unsigned char* lds, const WCtx& w, int l) {
;     ...
;             solve_diag(x, A22T, 32, 0, 31);
	v_fma_f32 v18, -v17, v18, v22
	v_fma_f32 v19, -v17, v19, v23
	v_fma_f32 v24, -v17, v20, v24
	v_fma_f32 v25, -v17, v21, v25
	ds_read_b128 v[20:23], v38 offset:16064
	v_fma_f32 v29, -v16, v29, v43
	v_fma_f32 v30, -v16, v30, v44
	v_fma_f32 v31, -v16, v31, v45
	s_waitcnt lgkmcnt(0)
	v_fma_f32 v26, -v17, v20, v26
	v_fma_f32 v27, -v17, v21, v27
	v_fma_f32 v28, -v17, v22, v28
	v_fma_f32 v29, -v17, v23, v29
	ds_read_b128 v[20:23], v38 offset:16080
	s_waitcnt lgkmcnt(0)
	v_fma_f32 v30, -v17, v20, v30
	v_fma_f32 v31, -v17, v21, v31
	v_fma_f32 v32, -v17, v22, v32
	v_fma_f32 v33, -v17, v23, v33
	ds_read_b128 v[20:23], v38 offset:16096
	s_waitcnt lgkmcnt(0)
	v_fma_f32 v34, -v17, v20, v34
	v_mov_b32_e32 v20, v51
	v_fma_f32 v35, -v17, v21, v35
	v_lshl_add_u32 v38, v20, 2, s27
	v_fma_f32 v36, -v17, v22, v36
	v_fma_f32 v37, -v17, v23, v37
	ds_read_b128 v[20:23], v38 offset:16192
	s_waitcnt lgkmcnt(0)
	v_fma_f32 v19, -v18, v21, v19
	v_fma_f32 v24, -v18, v22, v24
	v_fma_f32 v25, -v18, v23, v25
	ds_read_b128 v[20:23], v38 offset:16208
	s_waitcnt lgkmcnt(0)
	v_fma_f32 v26, -v18, v20, v26
	v_fma_f32 v27, -v18, v21, v27
	v_fma_f32 v28, -v18, v22, v28
	v_fma_f32 v29, -v18, v23, v29
	ds_read_b128 v[20:23], v38 offset:16224
	s_waitcnt lgkmcnt(0)
	v_fma_f32 v30, -v18, v20, v30
	v_fma_f32 v31, -v18, v21, v31
	v_fma_f32 v32, -v18, v22, v32
	v_fma_f32 v33, -v18, v23, v33
	ds_read_b128 v[20:23], v38 offset:16240
	s_waitcnt lgkmcnt(0)
	v_fma_f32 v34, -v18, v20, v34
	v_mov_b32_e32 v20, v51
	v_fma_f32 v35, -v18, v21, v35
	v_lshl_add_u32 v38, v20, 2, s27
	v_fma_f32 v36, -v18, v22, v36
	v_fma_f32 v37, -v18, v23, v37
	ds_read_b128 v[20:23], v38 offset:16336
	s_waitcnt lgkmcnt(0)
	v_fma_f32 v20, -v19, v22, v24
	v_fma_f32 v21, -v19, v23, v25
	ds_read_b128 v[22:25], v38 offset:16352
	s_waitcnt lgkmcnt(0)
	v_fma_f32 v26, -v19, v22, v26
	v_fma_f32 v27, -v19, v23, v27
	v_fma_f32 v28, -v19, v24, v28
	v_fma_f32 v29, -v19, v25, v29
	ds_read_b128 v[22:25], v38 offset:16368
	s_waitcnt lgkmcnt(0)
	v_fma_f32 v30, -v19, v22, v30
	v_fma_f32 v31, -v19, v23, v31
	v_fma_f32 v32, -v19, v24, v32
	v_fma_f32 v33, -v19, v25, v33
	ds_read_b128 v[22:25], v38 offset:16384
	s_waitcnt lgkmcnt(0)
	v_fma_f32 v34, -v19, v22, v34
	v_mov_b32_e32 v22, v51
	v_fma_f32 v35, -v19, v23, v35
	v_lshl_add_u32 v38, v22, 2, s27
	v_fma_f32 v36, -v19, v24, v36
	v_fma_f32 v37, -v19, v25, v37
	ds_read_b128 v[22:25], v38 offset:16480
	s_waitcnt lgkmcnt(0)
	v_fma_f32 v21, -v20, v25, v21
	ds_read_b128 v[22:25], v38 offset:16496
	s_waitcnt lgkmcnt(0)
	v_fma_f32 v26, -v20, v22, v26
	v_fma_f32 v27, -v20, v23, v27
	v_fma_f32 v28, -v20, v24, v28
	v_fma_f32 v29, -v20, v25, v29
	ds_read_b128 v[22:25], v38 offset:16512
	s_waitcnt lgkmcnt(0)
	v_fma_f32 v30, -v20, v22, v30
	v_fma_f32 v31, -v20, v23, v31
	v_fma_f32 v32, -v20, v24, v32
	v_fma_f32 v33, -v20, v25, v33
	ds_read_b128 v[22:25], v38 offset:16528
	s_waitcnt lgkmcnt(0)
	v_fma_f32 v34, -v20, v22, v34
	v_mov_b32_e32 v22, v51
	v_fma_f32 v35, -v20, v23, v35
	v_lshl_add_u32 v38, v22, 2, s27
	v_fma_f32 v36, -v20, v24, v36
	v_fma_f32 v37, -v20, v25, v37
	ds_read_b128 v[22:25], v38 offset:16640
	s_waitcnt lgkmcnt(0)
	v_fma_f32 v22, -v21, v22, v26
	v_fma_f32 v23, -v21, v23, v27
	v_fma_f32 v28, -v21, v24, v28
	v_fma_f32 v29, -v21, v25, v29
	ds_read_b128 v[24:27], v38 offset:16656
	s_waitcnt lgkmcnt(0)
	v_fma_f32 v30, -v21, v24, v30
	v_fma_f32 v31, -v21, v25, v31
	v_fma_f32 v32, -v21, v26, v32
	v_fma_f32 v33, -v21, v27, v33
	ds_read_b128 v[24:27], v38 offset:16672
	s_waitcnt lgkmcnt(0)
	v_fma_f32 v34, -v21, v24, v34
	v_mov_b32_e32 v24, v51
	v_fma_f32 v35, -v21, v25, v35
	v_lshl_add_u32 v38, v24, 2, s27
	v_fma_f32 v36, -v21, v26, v36
	v_fma_f32 v37, -v21, v27, v37
	ds_read_b128 v[24:27], v38 offset:16784
	s_waitcnt lgkmcnt(0)
	v_fma_f32 v23, -v22, v25, v23
	v_fma_f32 v28, -v22, v26, v28
	v_fma_f32 v29, -v22, v27, v29
	ds_read_b128 v[24:27], v38 offset:16800
	s_waitcnt lgkmcnt(0)
	v_fma_f32 v30, -v22, v24, v30
	v_fma_f32 v31, -v22, v25, v31
	v_fma_f32 v32, -v22, v26, v32
	v_fma_f32 v33, -v22, v27, v33
	ds_read_b128 v[24:27], v38 offset:16816
	s_waitcnt lgkmcnt(0)
	v_fma_f32 v34, -v22, v24, v34
	v_mov_b32_e32 v24, v51
	v_fma_f32 v35, -v22, v25, v35
	v_lshl_add_u32 v38, v24, 2, s27
	v_fma_f32 v36, -v22, v26, v36
	v_fma_f32 v37, -v22, v27, v37
	ds_read_b128 v[24:27], v38 offset:16928
	s_waitcnt lgkmcnt(0)
	v_fma_f32 v24, -v23, v26, v28
	v_fma_f32 v25, -v23, v27, v29
	ds_read_b128 v[26:29], v38 offset:16944
	s_waitcnt lgkmcnt(0)
	v_fma_f32 v30, -v23, v26, v30
	v_fma_f32 v31, -v23, v27, v31
	v_fma_f32 v32, -v23, v28, v32
	v_fma_f32 v33, -v23, v29, v33
	ds_read_b128 v[26:29], v38 offset:16960
	s_waitcnt lgkmcnt(0)
	v_fma_f32 v34, -v23, v26, v34
	v_mov_b32_e32 v26, v51
	v_fma_f32 v35, -v23, v27, v35
	v_lshl_add_u32 v38, v26, 2, s27
	v_fma_f32 v36, -v23, v28, v36
	v_fma_f32 v37, -v23, v29, v37
	ds_read_b128 v[26:29], v38 offset:17072
	s_waitcnt lgkmcnt(0)
	v_fma_f32 v25, -v24, v29, v25
	ds_read_b128 v[26:29], v38 offset:17088
	s_waitcnt lgkmcnt(0)
	v_fma_f32 v30, -v24, v26, v30
	v_fma_f32 v31, -v24, v27, v31
	v_fma_f32 v32, -v24, v28, v32
	v_fma_f32 v33, -v24, v29, v33
	ds_read_b128 v[26:29], v38 offset:17104
	s_waitcnt lgkmcnt(0)
	v_fma_f32 v34, -v24, v26, v34
	v_mov_b32_e32 v26, v51
	v_fma_f32 v35, -v24, v27, v35
	v_lshl_add_u32 v38, v26, 2, s27
	v_fma_f32 v36, -v24, v28, v36
	v_fma_f32 v37, -v24, v29, v37
	ds_read_b128 v[26:29], v38 offset:17232
	s_waitcnt lgkmcnt(0)
	v_fma_f32 v26, -v25, v26, v30
	v_fma_f32 v27, -v25, v27, v31
	v_fma_f32 v32, -v25, v28, v32
	v_fma_f32 v33, -v25, v29, v33
	ds_read_b128 v[28:31], v38 offset:17248
	s_waitcnt lgkmcnt(0)
; __device__ __forceinline__ unsigned f2bf(float f) { unsigned u = __float_as_uint(f); return (u + 0x7fffu + ((u >> 16) & 1u)) >> 16; }
; __device__ __forceinline__ unsigned cvt_pk_bf16(float lo, float hi) { unsigned r; asm volatile("v_cvt_pk_bf16_f32 %0, %1, %2" : "=v"(r) : "v"(lo), "v"(hi)); return r; }
; __device__ __forceinline__ void phase_gdn_solve(const Args& a, LAS unsigned char* lds, const WCtx& w, int l) {
;     ...
;             solve_diag(x, A22T, 32, 0, 31);
;             {
;                 if (wv == 0) { bf16* dst = UT + ((size_t)(chain * 36 + c) * 64 + lane) * 64;
; #pragma unroll
;                     for (int q = 0; q < 8; ++q) { v4u o; o.x = cvt_pk_bf16(x[8 * q], x[8 * q + 1]); o.y = cvt_pk_bf16(x[8 * q + 2], x[8 * q + 3]); o.z = cvt_pk_bf16(x[8 * q + 4], x[8 * q + 5]); o.w = cvt_pk_bf16(x[8 * q + 6], x[8 * q + 7]); *(v4u*)(dst + 8 * q) = o; } }
;                 else { bf16* dst = WW + (size_t)(chain * 36 + c) * 4096 + lane;
; #pragma unroll
;                     for (int j = 0; j < 64; ++j) dst[j * 64] = (bf16)f2bf(x[j]); }
	v_fma_f32 v34, -v25, v28, v34
	v_mov_b32_e32 v28, v51
	v_fma_f32 v35, -v25, v29, v35
	v_lshl_add_u32 v38, v28, 2, s27
	v_fma_f32 v36, -v25, v30, v36
	v_fma_f32 v37, -v25, v31, v37
	ds_read_b128 v[28:31], v38 offset:17376
	s_waitcnt lgkmcnt(0)
	v_fma_f32 v27, -v26, v29, v27
	v_fma_f32 v32, -v26, v30, v32
	v_fma_f32 v33, -v26, v31, v33
	ds_read_b128 v[28:31], v38 offset:17392
	s_waitcnt lgkmcnt(0)
	v_fma_f32 v34, -v26, v28, v34
	v_mov_b32_e32 v28, v51
	v_fma_f32 v35, -v26, v29, v35
	v_lshl_add_u32 v38, v28, 2, s27
	v_fma_f32 v36, -v26, v30, v36
	v_fma_f32 v37, -v26, v31, v37
	ds_read_b128 v[28:31], v38 offset:17520
	s_waitcnt lgkmcnt(0)
	v_fma_f32 v28, -v27, v30, v32
	v_fma_f32 v29, -v27, v31, v33
	ds_read_b128 v[30:33], v38 offset:17536
	s_waitcnt lgkmcnt(0)
	v_fma_f32 v34, -v27, v30, v34
	v_mov_b32_e32 v30, v51
	v_fma_f32 v35, -v27, v31, v35
	v_lshl_add_u32 v38, v30, 2, s27
	v_fma_f32 v36, -v27, v32, v36
	v_fma_f32 v37, -v27, v33, v37
	ds_read_b128 v[30:33], v38 offset:17664
	s_waitcnt lgkmcnt(0)
	v_fma_f32 v29, -v28, v33, v29
	ds_read_b128 v[30:33], v38 offset:17680
	s_waitcnt lgkmcnt(0)
	v_fma_f32 v34, -v28, v30, v34
	v_mov_b32_e32 v30, v51
	v_fma_f32 v35, -v28, v31, v35
	v_lshl_add_u32 v30, v30, 2, s27
	v_fma_f32 v36, -v28, v32, v36
	v_fma_f32 v37, -v28, v33, v37
	ds_read_b128 v[30:33], v30 offset:17824
	s_waitcnt lgkmcnt(0)
	v_fma_f32 v36, -v29, v32, v36
	v_mov_b32_e32 v32, v51
	v_fma_f32 v30, -v29, v30, v34
	v_lshl_add_u32 v32, v32, 2, s27
	v_fma_f32 v31, -v29, v31, v35
	v_fma_f32 v37, -v29, v33, v37
	ds_read_b128 v[32:35], v32 offset:17968
	s_waitcnt lgkmcnt(0)
	v_mov_b32_e32 v32, v51
	v_fma_f32 v31, -v30, v33, v31
	v_lshl_add_u32 v32, v32, 2, s27
	v_fma_f32 v36, -v30, v34, v36
	v_fma_f32 v37, -v30, v35, v37
	ds_read_b128 v[32:35], v32 offset:18112
	s_waitcnt lgkmcnt(0)
	v_fma_f32 v32, -v31, v34, v36
	v_mov_b32_e32 v34, v51
	v_fma_f32 v33, -v31, v35, v37
	v_lshl_add_u32 v34, v34, 2, s27
	ds_read_b128 v[34:37], v34 offset:18256
	s_waitcnt lgkmcnt(0)
	v_fma_f32 v33, -v32, v37, v33
	s_cbranch_vccz .LBB0_1065
	v_readlane_b32 s2, v253, 57
	v_readlane_b32 s3, v253, 58
	s_add_u32 s2, s2, s0
	v_bfe_u32 v36, v163, 16, 1
	s_movk_i32 s10, 0x7fff
	s_addc_u32 s3, s3, s1
	v_add3_u32 v36, v163, v36, s10
	global_store_short_d16_hi v50, v36, s[2:3]
	v_bfe_u32 v36, v156, 16, 1
	v_add3_u32 v36, v156, v36, s10
	global_store_short_d16_hi v50, v36, s[2:3] offset:128
	v_bfe_u32 v36, v164, 16, 1
	v_add3_u32 v36, v164, v36, s10
	global_store_short_d16_hi v50, v36, s[2:3] offset:256
	v_bfe_u32 v36, v152, 16, 1
	v_add3_u32 v36, v152, v36, s10
	global_store_short_d16_hi v50, v36, s[2:3] offset:384
	v_bfe_u32 v36, v167, 16, 1
	v_add3_u32 v36, v167, v36, s10
	global_store_short_d16_hi v50, v36, s[2:3] offset:512
	v_bfe_u32 v36, v154, 16, 1
	v_add3_u32 v36, v154, v36, s10
	global_store_short_d16_hi v50, v36, s[2:3] offset:640
	v_bfe_u32 v36, v168, 16, 1
	v_add3_u32 v36, v168, v36, s10
	global_store_short_d16_hi v50, v36, s[2:3] offset:768
	v_bfe_u32 v36, v158, 16, 1
	v_add3_u32 v36, v158, v36, s10
	global_store_short_d16_hi v50, v36, s[2:3] offset:896
	v_bfe_u32 v36, v170, 16, 1
	v_add3_u32 v36, v170, v36, s10
	global_store_short_d16_hi v50, v36, s[2:3] offset:1024
	v_bfe_u32 v36, v148, 16, 1
	v_add3_u32 v36, v148, v36, s10
	global_store_short_d16_hi v50, v36, s[2:3] offset:1152
	v_bfe_u32 v36, v172, 16, 1
	v_add3_u32 v36, v172, v36, s10
	global_store_short_d16_hi v50, v36, s[2:3] offset:1280
	v_bfe_u32 v36, v150, 16, 1
	v_add3_u32 v36, v150, v36, s10
	global_store_short_d16_hi v50, v36, s[2:3] offset:1408
	v_bfe_u32 v36, v141, 16, 1
	v_add3_u32 v36, v141, v36, s10
	global_store_short_d16_hi v50, v36, s[2:3] offset:1536
	v_bfe_u32 v36, v136, 16, 1
	v_add3_u32 v36, v136, v36, s10
	global_store_short_d16_hi v50, v36, s[2:3] offset:1664
	v_bfe_u32 v36, v142, 16, 1
	v_add3_u32 v36, v142, v36, s10
	global_store_short_d16_hi v50, v36, s[2:3] offset:1792
	v_bfe_u32 v36, v138, 16, 1
	v_add3_u32 v36, v138, v36, s10
	global_store_short_d16_hi v50, v36, s[2:3] offset:1920
	v_bfe_u32 v36, v92, 16, 1
	v_add3_u32 v36, v92, v36, s10
	global_store_short_d16_hi v50, v36, s[2:3] offset:2048
	v_bfe_u32 v36, v60, 16, 1
	v_add3_u32 v36, v60, v36, s10
	global_store_short_d16_hi v50, v36, s[2:3] offset:2176
	v_bfe_u32 v36, v76, 16, 1
	v_add3_u32 v36, v76, v36, s10
	global_store_short_d16_hi v50, v36, s[2:3] offset:2304
	v_bfe_u32 v36, v120, 16, 1
	v_add3_u32 v36, v120, v36, s10
	global_store_short_d16_hi v50, v36, s[2:3] offset:2432
	v_bfe_u32 v36, v79, 16, 1
	v_add3_u32 v36, v79, v36, s10
	global_store_short_d16_hi v50, v36, s[2:3] offset:2560
	v_bfe_u32 v36, v126, 16, 1
	v_add3_u32 v36, v126, v36, s10
	global_store_short_d16_hi v50, v36, s[2:3] offset:2688
	v_bfe_u32 v36, v68, 16, 1
	v_add3_u32 v36, v68, v36, s10
	global_store_short_d16_hi v50, v36, s[2:3] offset:2816
	v_bfe_u32 v36, v160, 16, 1
	v_add3_u32 v36, v160, v36, s10
	global_store_short_d16_hi v50, v36, s[2:3] offset:2944
	v_bfe_u32 v36, v70, 16, 1
	v_add3_u32 v36, v70, v36, s10
	global_store_short_d16_hi v50, v36, s[2:3] offset:3072
; __device__ __forceinline__ unsigned f2bf(float f) { unsigned u = __float_as_uint(f); return (u + 0x7fffu + ((u >> 16) & 1u)) >> 16; }
; __device__ __forceinline__ void phase_gdn_solve(const Args& a, LAS unsigned char* lds, const WCtx& w, int l) {
;     ...
;                 else { bf16* dst = WW + (size_t)(chain * 36 + c) * 4096 + lane;
; #pragma unroll
;                     for (int j = 0; j < 64; ++j) dst[j * 64] = (bf16)f2bf(x[j]); }
	v_bfe_u32 v36, v64, 16, 1
	v_add3_u32 v36, v64, v36, s10
	global_store_short_d16_hi v50, v36, s[2:3] offset:3200
	v_bfe_u32 v36, v66, 16, 1
	v_add3_u32 v36, v66, v36, s10
	global_store_short_d16_hi v50, v36, s[2:3] offset:3328
	v_bfe_u32 v36, v62, 16, 1
	v_add3_u32 v36, v62, v36, s10
	global_store_short_d16_hi v50, v36, s[2:3] offset:3456
	v_bfe_u32 v36, v73, 16, 1
	v_add3_u32 v36, v73, v36, s10
	global_store_short_d16_hi v50, v36, s[2:3] offset:3584
	v_bfe_u32 v36, v122, 16, 1
	v_add3_u32 v36, v122, v36, s10
	global_store_short_d16_hi v50, v36, s[2:3] offset:3712
	v_bfe_u32 v36, v124, 16, 1
	v_add3_u32 v36, v124, v36, s10
	global_store_short_d16_hi v50, v36, s[2:3] offset:3840
	v_bfe_u32 v36, v96, 16, 1
	v_add3_u32 v36, v96, v36, s10
	v_lshl_add_u64 v[34:35], s[2:3], 0, v[50:51]
	global_store_short_d16_hi v50, v36, s[2:3] offset:3968
	s_movk_i32 s2, 0x1000
	v_bfe_u32 v36, v2, 16, 1
	v_add_co_u32_e32 v34, vcc, s2, v34
	v_add3_u32 v36, v2, v36, s10
	s_nop 0
	v_addc_co_u32_e32 v35, vcc, 0, v35, vcc
	global_store_short_d16_hi v[34:35], v36, off
	v_bfe_u32 v36, v3, 16, 1
	v_add3_u32 v36, v3, v36, s10
	global_store_short_d16_hi v[34:35], v36, off offset:128
	v_bfe_u32 v36, v4, 16, 1
	v_add3_u32 v36, v4, v36, s10
	global_store_short_d16_hi v[34:35], v36, off offset:256
	v_bfe_u32 v36, v5, 16, 1
	v_add3_u32 v36, v5, v36, s10
	global_store_short_d16_hi v[34:35], v36, off offset:384
	v_bfe_u32 v36, v6, 16, 1
	v_add3_u32 v36, v6, v36, s10
	global_store_short_d16_hi v[34:35], v36, off offset:512
	v_bfe_u32 v36, v7, 16, 1
	v_add3_u32 v36, v7, v36, s10
	global_store_short_d16_hi v[34:35], v36, off offset:640
	v_bfe_u32 v36, v8, 16, 1
	v_add3_u32 v36, v8, v36, s10
	global_store_short_d16_hi v[34:35], v36, off offset:768
	v_bfe_u32 v36, v9, 16, 1
	v_add3_u32 v36, v9, v36, s10
	global_store_short_d16_hi v[34:35], v36, off offset:896
	v_bfe_u32 v36, v10, 16, 1
	v_add3_u32 v36, v10, v36, s10
	global_store_short_d16_hi v[34:35], v36, off offset:1024
	v_bfe_u32 v36, v11, 16, 1
	v_add3_u32 v36, v11, v36, s10
	global_store_short_d16_hi v[34:35], v36, off offset:1152
	v_bfe_u32 v36, v12, 16, 1
	v_add3_u32 v36, v12, v36, s10
	global_store_short_d16_hi v[34:35], v36, off offset:1280
	v_bfe_u32 v36, v13, 16, 1
	v_add3_u32 v36, v13, v36, s10
	global_store_short_d16_hi v[34:35], v36, off offset:1408
	v_bfe_u32 v36, v14, 16, 1
	v_add3_u32 v36, v14, v36, s10
	global_store_short_d16_hi v[34:35], v36, off offset:1536
	v_bfe_u32 v36, v15, 16, 1
	v_add3_u32 v36, v15, v36, s10
	global_store_short_d16_hi v[34:35], v36, off offset:1664
	v_bfe_u32 v36, v16, 16, 1
	v_add3_u32 v36, v16, v36, s10
	global_store_short_d16_hi v[34:35], v36, off offset:1792
	v_bfe_u32 v36, v17, 16, 1
	v_add3_u32 v36, v17, v36, s10
	global_store_short_d16_hi v[34:35], v36, off offset:1920
	v_bfe_u32 v36, v18, 16, 1
	v_add3_u32 v36, v18, v36, s10
	global_store_short_d16_hi v[34:35], v36, off offset:2048
	v_bfe_u32 v36, v19, 16, 1
	v_add3_u32 v36, v19, v36, s10
	global_store_short_d16_hi v[34:35], v36, off offset:2176
	v_bfe_u32 v36, v20, 16, 1
	v_add3_u32 v36, v20, v36, s10
	global_store_short_d16_hi v[34:35], v36, off offset:2304
	v_bfe_u32 v36, v21, 16, 1
	v_add3_u32 v36, v21, v36, s10
	global_store_short_d16_hi v[34:35], v36, off offset:2432
	v_bfe_u32 v36, v22, 16, 1
	v_add3_u32 v36, v22, v36, s10
	global_store_short_d16_hi v[34:35], v36, off offset:2560
	v_bfe_u32 v36, v23, 16, 1
	v_add3_u32 v36, v23, v36, s10
	global_store_short_d16_hi v[34:35], v36, off offset:2688
	v_bfe_u32 v36, v24, 16, 1
	v_add3_u32 v36, v24, v36, s10
	global_store_short_d16_hi v[34:35], v36, off offset:2816
	v_bfe_u32 v36, v25, 16, 1
	v_add3_u32 v36, v25, v36, s10
	global_store_short_d16_hi v[34:35], v36, off offset:2944
	v_bfe_u32 v36, v26, 16, 1
	v_add3_u32 v36, v26, v36, s10
	global_store_short_d16_hi v[34:35], v36, off offset:3072
	v_bfe_u32 v36, v27, 16, 1
	v_add3_u32 v36, v27, v36, s10
	global_store_short_d16_hi v[34:35], v36, off offset:3200
	v_bfe_u32 v36, v28, 16, 1
	v_add3_u32 v36, v28, v36, s10
	global_store_short_d16_hi v[34:35], v36, off offset:3328
	v_bfe_u32 v36, v29, 16, 1
	v_add3_u32 v36, v29, v36, s10
	global_store_short_d16_hi v[34:35], v36, off offset:3456
	v_bfe_u32 v36, v30, 16, 1
	v_add3_u32 v36, v30, v36, s10
	global_store_short_d16_hi v[34:35], v36, off offset:3584
	v_bfe_u32 v36, v31, 16, 1
	v_add3_u32 v36, v31, v36, s10
	global_store_short_d16_hi v[34:35], v36, off offset:3712
	v_bfe_u32 v36, v32, 16, 1
	v_add3_u32 v36, v32, v36, s10
	global_store_short_d16_hi v[34:35], v36, off offset:3840
	v_bfe_u32 v36, v33, 16, 1
	v_add3_u32 v36, v33, v36, s10
	global_store_short_d16_hi v[34:35], v36, off offset:3968
	v_mov_b32_e32 v123, v73
	v_mov_b32_e32 v63, v66
	v_mov_b32_e32 v65, v70
	v_mov_b32_e32 v161, v68
	v_mov_b32_e32 v127, v79
	v_mov_b32_e32 v121, v76
	v_mov_b32_e32 v61, v92
	v_mov_b32_e32 v139, v142
	v_mov_b32_e32 v137, v141
	v_mov_b32_e32 v151, v172
	v_mov_b32_e32 v149, v170
	v_mov_b32_e32 v159, v168
	v_mov_b32_e32 v155, v167
	v_mov_b32_e32 v153, v164
	v_mov_b32_e32 v157, v163
	s_mov_b64 s[2:3], 0
	s_branch .LBB0_1066
